# v16 + conv_phase rewritten by hand: per-wave scalar chunk control, 11-row rolling prefetch ring with counted vmcnt, packed f32 FMA (same f32 math, different association)
# baseline (speedup 1.0000x reference)
.LBB0_934:
	s_or_b64 exec, exec, s[34:35]
	s_mul_i32 s2, s62, 0x6000
	s_waitcnt lgkmcnt(0)
	s_barrier
	s_load_dwordx2 s[4:5], s[74:75], 0x98
	s_load_dwordx2 s[6:7], s[74:75], 32
	v_readfirstlane_b32 s8, v210
	v_and_b32_e32 v0, 0xff, v210
	v_lshlrev_b32_e32 v1, 5, v0
	v_lshlrev_b32_e32 v2, 4, v0
	s_lshr_b32 s8, s8, 8
	s_lshl_b32 s9, s73, 1
	s_add_i32 s9, s9, s8
	s_waitcnt lgkmcnt(0)
	s_cmp_gt_u32 s9, 498
	s_cbranch_scc1 .Lconv_skip
	s_mul_i32 s10, s9, 33
	s_mov_b32 s11, s10
	s_sub_i32 s12, s11, 0x1010
	s_cmp_ge_i32 s11, 0x1010
	s_cselect_b32 s11, s12, s11
	s_sub_i32 s12, s11, 0x1010
	s_cmp_ge_i32 s11, 0x1010
	s_cselect_b32 s11, s12, s11
	s_sub_i32 s12, s11, 0x1010
	s_cmp_ge_i32 s11, 0x1010
	s_cselect_b32 s11, s12, s11
	s_sub_i32 s12, s11, 0x1010
	s_cmp_ge_i32 s11, 0x1010
	s_cselect_b32 s11, s12, s11
	s_mul_i32 s12, s62, 0x6000
	s_add_u32 s6, s6, s12
	s_addc_u32 s7, s7, 0
	global_load_dwordx4 v[4:7], v1, s[6:7]
	global_load_dwordx4 v[8:11], v1, s[6:7] offset:16
	s_add_u32 s12, s6, 0x2000
	s_addc_u32 s13, s7, 0
	global_load_dwordx4 v[12:15], v1, s[12:13]
	global_load_dwordx4 v[16:19], v1, s[12:13] offset:16
	s_add_u32 s12, s6, 0x4000
	s_addc_u32 s13, s7, 0
	global_load_dwordx4 v[20:23], v1, s[12:13]
	global_load_dwordx4 v[24:27], v1, s[12:13] offset:16
	s_lshl_b32 s14, s10, 12
	s_add_u32 s16, s4, 0x2efd0000
	s_addc_u32 s17, s5, 0
	s_add_u32 s16, s16, s14
	s_addc_u32 s17, s17, 0
	s_add_u32 s18, s4, 0x330d0000
	s_addc_u32 s19, s5, 0
	s_add_u32 s18, s18, s14
	s_addc_u32 s19, s19, 0
	s_add_u32 s20, s4, 0x371d0000
	s_addc_u32 s21, s5, 0
	s_add_u32 s20, s20, s14
	s_addc_u32 s21, s21, 0
	s_add_u32 s22, s18, 0xfffff000
	s_addc_u32 s23, s19, -1
	s_add_u32 s24, s18, 0xffffe000
	s_addc_u32 s25, s19, -1
	global_load_dwordx4 v[52:55], v2, s[22:23]
	global_load_dwordx4 v[56:59], v2, s[24:25]
	global_load_dwordx4 v[68:71], v2, s[18:19]
	global_load_dwordx4 v[72:75], v2, s[16:17]
	s_add_u32 s18, s18, 0x1000
	s_addc_u32 s19, s19, 0
	s_add_u32 s16, s16, 0x1000
	s_addc_u32 s17, s17, 0
	global_load_dwordx4 v[76:79], v2, s[18:19]
	global_load_dwordx4 v[80:83], v2, s[16:17]
	s_add_u32 s18, s18, 0x1000
	s_addc_u32 s19, s19, 0
	s_add_u32 s16, s16, 0x1000
	s_addc_u32 s17, s17, 0
	global_load_dwordx4 v[84:87], v2, s[18:19]
	global_load_dwordx4 v[88:91], v2, s[16:17]
	s_add_u32 s18, s18, 0x1000
	s_addc_u32 s19, s19, 0
	s_add_u32 s16, s16, 0x1000
	s_addc_u32 s17, s17, 0
	global_load_dwordx4 v[92:95], v2, s[18:19]
	global_load_dwordx4 v[96:99], v2, s[16:17]
	s_add_u32 s18, s18, 0x1000
	s_addc_u32 s19, s19, 0
	s_add_u32 s16, s16, 0x1000
	s_addc_u32 s17, s17, 0
	global_load_dwordx4 v[100:103], v2, s[18:19]
	global_load_dwordx4 v[104:107], v2, s[16:17]
	s_add_u32 s18, s18, 0x1000
	s_addc_u32 s19, s19, 0
	s_add_u32 s16, s16, 0x1000
	s_addc_u32 s17, s17, 0
	global_load_dwordx4 v[108:111], v2, s[18:19]
	global_load_dwordx4 v[112:115], v2, s[16:17]
	s_add_u32 s18, s18, 0x1000
	s_addc_u32 s19, s19, 0
	s_add_u32 s16, s16, 0x1000
	s_addc_u32 s17, s17, 0
	global_load_dwordx4 v[116:119], v2, s[18:19]
	global_load_dwordx4 v[120:123], v2, s[16:17]
	s_add_u32 s18, s18, 0x1000
	s_addc_u32 s19, s19, 0
	s_add_u32 s16, s16, 0x1000
	s_addc_u32 s17, s17, 0
	global_load_dwordx4 v[132:135], v2, s[18:19]
	global_load_dwordx4 v[136:139], v2, s[16:17]
	s_add_u32 s18, s18, 0x1000
	s_addc_u32 s19, s19, 0
	s_add_u32 s16, s16, 0x1000
	s_addc_u32 s17, s17, 0
	global_load_dwordx4 v[140:143], v2, s[18:19]
	global_load_dwordx4 v[144:147], v2, s[16:17]
	s_add_u32 s18, s18, 0x1000
	s_addc_u32 s19, s19, 0
	s_add_u32 s16, s16, 0x1000
	s_addc_u32 s17, s17, 0
	global_load_dwordx4 v[148:151], v2, s[18:19]
	global_load_dwordx4 v[152:155], v2, s[16:17]
	s_add_u32 s18, s18, 0x1000
	s_addc_u32 s19, s19, 0
	s_add_u32 s16, s16, 0x1000
	s_addc_u32 s17, s17, 0
	global_load_dwordx4 v[156:159], v2, s[18:19]
	global_load_dwordx4 v[160:163], v2, s[16:17]
	s_add_u32 s18, s18, 0x1000
	s_addc_u32 s19, s19, 0
	s_add_u32 s16, s16, 0x1000
	s_addc_u32 s17, s17, 0
	s_waitcnt vmcnt(20)
	v_lshlrev_b32_e32 v44, 16, v52
	v_and_b32_e32 v45, 0xffff0000, v52
	v_lshlrev_b32_e32 v36, 16, v56
	v_and_b32_e32 v37, 0xffff0000, v56
	v_lshlrev_b32_e32 v46, 16, v53
	v_and_b32_e32 v47, 0xffff0000, v53
	v_lshlrev_b32_e32 v38, 16, v57
	v_and_b32_e32 v39, 0xffff0000, v57
	v_lshlrev_b32_e32 v48, 16, v54
	v_and_b32_e32 v49, 0xffff0000, v54
	v_lshlrev_b32_e32 v40, 16, v58
	v_and_b32_e32 v41, 0xffff0000, v58
	v_lshlrev_b32_e32 v50, 16, v55
	v_and_b32_e32 v51, 0xffff0000, v55
	v_lshlrev_b32_e32 v42, 16, v59
	v_and_b32_e32 v43, 0xffff0000, v59
	s_cmp_lt_u32 s11, 2
	s_cbranch_scc0 .Lconv_um2ok
	v_mov_b32_e32 v36, 0
	v_mov_b32_e32 v37, 0
	v_mov_b32_e32 v38, 0
	v_mov_b32_e32 v39, 0
	v_mov_b32_e32 v40, 0
	v_mov_b32_e32 v41, 0
	v_mov_b32_e32 v42, 0
	v_mov_b32_e32 v43, 0
.Lconv_um2ok:
	s_cmp_eq_u32 s11, 0
	s_cbranch_scc0 .Lconv_nz0
	v_mov_b32_e32 v44, 0
	v_mov_b32_e32 v45, 0
	v_mov_b32_e32 v46, 0
	v_mov_b32_e32 v47, 0
	v_mov_b32_e32 v48, 0
	v_mov_b32_e32 v49, 0
	v_mov_b32_e32 v50, 0
	v_mov_b32_e32 v51, 0
	v_mov_b32_e32 v36, 0
	v_mov_b32_e32 v37, 0
	v_mov_b32_e32 v38, 0
	v_mov_b32_e32 v39, 0
	v_mov_b32_e32 v40, 0
	v_mov_b32_e32 v41, 0
	v_mov_b32_e32 v42, 0
	v_mov_b32_e32 v43, 0
.Lconv_nz0:
	v_lshlrev_b32_e32 v28, 16, v68
	v_and_b32_e32 v29, 0xffff0000, v68
	v_lshlrev_b32_e32 v30, 16, v69
	v_and_b32_e32 v31, 0xffff0000, v69
	v_lshlrev_b32_e32 v32, 16, v70
	v_and_b32_e32 v33, 0xffff0000, v70
	v_lshlrev_b32_e32 v34, 16, v71
	v_and_b32_e32 v35, 0xffff0000, v71
	v_lshlrev_b32_e32 v52, 16, v72
	v_and_b32_e32 v53, 0xffff0000, v72
	v_lshlrev_b32_e32 v54, 16, v73
	v_and_b32_e32 v55, 0xffff0000, v73
	v_lshlrev_b32_e32 v56, 16, v74
	v_and_b32_e32 v57, 0xffff0000, v74
	v_lshlrev_b32_e32 v58, 16, v75
	v_and_b32_e32 v59, 0xffff0000, v75
	v_pk_mul_f32 v[60:61], v[4:5], v[36:37]
	v_pk_mul_f32 v[62:63], v[6:7], v[38:39]
	v_pk_mul_f32 v[64:65], v[8:9], v[40:41]
	v_pk_mul_f32 v[66:67], v[10:11], v[42:43]
	v_pk_fma_f32 v[60:61], v[12:13], v[44:45], v[60:61]
	v_pk_fma_f32 v[62:63], v[14:15], v[46:47], v[62:63]
	v_pk_fma_f32 v[64:65], v[16:17], v[48:49], v[64:65]
	v_pk_fma_f32 v[66:67], v[18:19], v[50:51], v[66:67]
	v_pk_fma_f32 v[60:61], v[20:21], v[28:29], v[60:61]
	v_pk_fma_f32 v[62:63], v[22:23], v[30:31], v[62:63]
	v_pk_fma_f32 v[64:65], v[24:25], v[32:33], v[64:65]
	v_pk_fma_f32 v[66:67], v[26:27], v[34:35], v[66:67]
	v_pk_mul_f32 v[60:61], v[60:61], v[52:53]
	v_pk_mul_f32 v[62:63], v[62:63], v[54:55]
	v_pk_mul_f32 v[64:65], v[64:65], v[56:57]
	v_pk_mul_f32 v[66:67], v[66:67], v[58:59]
	v_cvt_pk_bf16_f32 v68, v60, v61
	v_cvt_pk_bf16_f32 v69, v62, v63
	v_cvt_pk_bf16_f32 v70, v64, v65
	v_cvt_pk_bf16_f32 v71, v66, v67
	global_store_dwordx4 v2, v[68:71], s[20:21]
	s_add_u32 s20, s20, 0x1000
	s_addc_u32 s21, s21, 0
	s_add_i32 s11, s11, 1
	s_cmp_eq_u32 s11, 0x1010
	s_cselect_b32 s11, 0, s11
	global_load_dwordx4 v[68:71], v2, s[18:19]
	global_load_dwordx4 v[72:75], v2, s[16:17]
	s_add_u32 s18, s18, 0x1000
	s_addc_u32 s19, s19, 0
	s_add_u32 s16, s16, 0x1000
	s_addc_u32 s17, s17, 0
	s_waitcnt vmcnt(21)
	s_cmp_eq_u32 s11, 0
	s_cbranch_scc0 .Lconv_nz1
	v_mov_b32_e32 v28, 0
	v_mov_b32_e32 v29, 0
	v_mov_b32_e32 v30, 0
	v_mov_b32_e32 v31, 0
	v_mov_b32_e32 v32, 0
	v_mov_b32_e32 v33, 0
	v_mov_b32_e32 v34, 0
	v_mov_b32_e32 v35, 0
	v_mov_b32_e32 v44, 0
	v_mov_b32_e32 v45, 0
	v_mov_b32_e32 v46, 0
	v_mov_b32_e32 v47, 0
	v_mov_b32_e32 v48, 0
	v_mov_b32_e32 v49, 0
	v_mov_b32_e32 v50, 0
	v_mov_b32_e32 v51, 0
.Lconv_nz1:
	v_lshlrev_b32_e32 v36, 16, v76
	v_and_b32_e32 v37, 0xffff0000, v76
	v_lshlrev_b32_e32 v38, 16, v77
	v_and_b32_e32 v39, 0xffff0000, v77
	v_lshlrev_b32_e32 v40, 16, v78
	v_and_b32_e32 v41, 0xffff0000, v78
	v_lshlrev_b32_e32 v42, 16, v79
	v_and_b32_e32 v43, 0xffff0000, v79
	v_lshlrev_b32_e32 v52, 16, v80
	v_and_b32_e32 v53, 0xffff0000, v80
	v_lshlrev_b32_e32 v54, 16, v81
	v_and_b32_e32 v55, 0xffff0000, v81
	v_lshlrev_b32_e32 v56, 16, v82
	v_and_b32_e32 v57, 0xffff0000, v82
	v_lshlrev_b32_e32 v58, 16, v83
	v_and_b32_e32 v59, 0xffff0000, v83
	v_pk_mul_f32 v[60:61], v[4:5], v[44:45]
	v_pk_mul_f32 v[62:63], v[6:7], v[46:47]
	v_pk_mul_f32 v[64:65], v[8:9], v[48:49]
	v_pk_mul_f32 v[66:67], v[10:11], v[50:51]
	v_pk_fma_f32 v[60:61], v[12:13], v[28:29], v[60:61]
	v_pk_fma_f32 v[62:63], v[14:15], v[30:31], v[62:63]
	v_pk_fma_f32 v[64:65], v[16:17], v[32:33], v[64:65]
	v_pk_fma_f32 v[66:67], v[18:19], v[34:35], v[66:67]
	v_pk_fma_f32 v[60:61], v[20:21], v[36:37], v[60:61]
	v_pk_fma_f32 v[62:63], v[22:23], v[38:39], v[62:63]
	v_pk_fma_f32 v[64:65], v[24:25], v[40:41], v[64:65]
	v_pk_fma_f32 v[66:67], v[26:27], v[42:43], v[66:67]
	v_pk_mul_f32 v[60:61], v[60:61], v[52:53]
	v_pk_mul_f32 v[62:63], v[62:63], v[54:55]
	v_pk_mul_f32 v[64:65], v[64:65], v[56:57]
	v_pk_mul_f32 v[66:67], v[66:67], v[58:59]
	v_cvt_pk_bf16_f32 v76, v60, v61
	v_cvt_pk_bf16_f32 v77, v62, v63
	v_cvt_pk_bf16_f32 v78, v64, v65
	v_cvt_pk_bf16_f32 v79, v66, v67
	global_store_dwordx4 v2, v[76:79], s[20:21]
	s_add_u32 s20, s20, 0x1000
	s_addc_u32 s21, s21, 0
	s_add_i32 s11, s11, 1
	s_cmp_eq_u32 s11, 0x1010
	s_cselect_b32 s11, 0, s11
	global_load_dwordx4 v[76:79], v2, s[18:19]
	global_load_dwordx4 v[80:83], v2, s[16:17]
	s_add_u32 s18, s18, 0x1000
	s_addc_u32 s19, s19, 0
	s_add_u32 s16, s16, 0x1000
	s_addc_u32 s17, s17, 0
	s_waitcnt vmcnt(22)
	s_cmp_eq_u32 s11, 0
	s_cbranch_scc0 .Lconv_nz2
	v_mov_b32_e32 v36, 0
	v_mov_b32_e32 v37, 0
	v_mov_b32_e32 v38, 0
	v_mov_b32_e32 v39, 0
	v_mov_b32_e32 v40, 0
	v_mov_b32_e32 v41, 0
	v_mov_b32_e32 v42, 0
	v_mov_b32_e32 v43, 0
	v_mov_b32_e32 v28, 0
	v_mov_b32_e32 v29, 0
	v_mov_b32_e32 v30, 0
	v_mov_b32_e32 v31, 0
	v_mov_b32_e32 v32, 0
	v_mov_b32_e32 v33, 0
	v_mov_b32_e32 v34, 0
	v_mov_b32_e32 v35, 0
.Lconv_nz2:
	v_lshlrev_b32_e32 v44, 16, v84
	v_and_b32_e32 v45, 0xffff0000, v84
	v_lshlrev_b32_e32 v46, 16, v85
	v_and_b32_e32 v47, 0xffff0000, v85
	v_lshlrev_b32_e32 v48, 16, v86
	v_and_b32_e32 v49, 0xffff0000, v86
	v_lshlrev_b32_e32 v50, 16, v87
	v_and_b32_e32 v51, 0xffff0000, v87
	v_lshlrev_b32_e32 v52, 16, v88
	v_and_b32_e32 v53, 0xffff0000, v88
	v_lshlrev_b32_e32 v54, 16, v89
	v_and_b32_e32 v55, 0xffff0000, v89
	v_lshlrev_b32_e32 v56, 16, v90
	v_and_b32_e32 v57, 0xffff0000, v90
	v_lshlrev_b32_e32 v58, 16, v91
	v_and_b32_e32 v59, 0xffff0000, v91
	v_pk_mul_f32 v[60:61], v[4:5], v[28:29]
	v_pk_mul_f32 v[62:63], v[6:7], v[30:31]
	v_pk_mul_f32 v[64:65], v[8:9], v[32:33]
	v_pk_mul_f32 v[66:67], v[10:11], v[34:35]
	v_pk_fma_f32 v[60:61], v[12:13], v[36:37], v[60:61]
	v_pk_fma_f32 v[62:63], v[14:15], v[38:39], v[62:63]
	v_pk_fma_f32 v[64:65], v[16:17], v[40:41], v[64:65]
	v_pk_fma_f32 v[66:67], v[18:19], v[42:43], v[66:67]
	v_pk_fma_f32 v[60:61], v[20:21], v[44:45], v[60:61]
	v_pk_fma_f32 v[62:63], v[22:23], v[46:47], v[62:63]
	v_pk_fma_f32 v[64:65], v[24:25], v[48:49], v[64:65]
	v_pk_fma_f32 v[66:67], v[26:27], v[50:51], v[66:67]
	v_pk_mul_f32 v[60:61], v[60:61], v[52:53]
	v_pk_mul_f32 v[62:63], v[62:63], v[54:55]
	v_pk_mul_f32 v[64:65], v[64:65], v[56:57]
	v_pk_mul_f32 v[66:67], v[66:67], v[58:59]
	v_cvt_pk_bf16_f32 v84, v60, v61
	v_cvt_pk_bf16_f32 v85, v62, v63
	v_cvt_pk_bf16_f32 v86, v64, v65
	v_cvt_pk_bf16_f32 v87, v66, v67
	global_store_dwordx4 v2, v[84:87], s[20:21]
	s_add_u32 s20, s20, 0x1000
	s_addc_u32 s21, s21, 0
	s_add_i32 s11, s11, 1
	s_cmp_eq_u32 s11, 0x1010
	s_cselect_b32 s11, 0, s11
	global_load_dwordx4 v[84:87], v2, s[18:19]
	global_load_dwordx4 v[88:91], v2, s[16:17]
	s_add_u32 s18, s18, 0x1000
	s_addc_u32 s19, s19, 0
	s_add_u32 s16, s16, 0x1000
	s_addc_u32 s17, s17, 0
	s_waitcnt vmcnt(23)
	s_cmp_eq_u32 s11, 0
	s_cbranch_scc0 .Lconv_nz3
	v_mov_b32_e32 v44, 0
	v_mov_b32_e32 v45, 0
	v_mov_b32_e32 v46, 0
	v_mov_b32_e32 v47, 0
	v_mov_b32_e32 v48, 0
	v_mov_b32_e32 v49, 0
	v_mov_b32_e32 v50, 0
	v_mov_b32_e32 v51, 0
	v_mov_b32_e32 v36, 0
	v_mov_b32_e32 v37, 0
	v_mov_b32_e32 v38, 0
	v_mov_b32_e32 v39, 0
	v_mov_b32_e32 v40, 0
	v_mov_b32_e32 v41, 0
	v_mov_b32_e32 v42, 0
	v_mov_b32_e32 v43, 0
.Lconv_nz3:
	v_lshlrev_b32_e32 v28, 16, v92
	v_and_b32_e32 v29, 0xffff0000, v92
	v_lshlrev_b32_e32 v30, 16, v93
	v_and_b32_e32 v31, 0xffff0000, v93
	v_lshlrev_b32_e32 v32, 16, v94
	v_and_b32_e32 v33, 0xffff0000, v94
	v_lshlrev_b32_e32 v34, 16, v95
	v_and_b32_e32 v35, 0xffff0000, v95
	v_lshlrev_b32_e32 v52, 16, v96
	v_and_b32_e32 v53, 0xffff0000, v96
	v_lshlrev_b32_e32 v54, 16, v97
	v_and_b32_e32 v55, 0xffff0000, v97
	v_lshlrev_b32_e32 v56, 16, v98
	v_and_b32_e32 v57, 0xffff0000, v98
	v_lshlrev_b32_e32 v58, 16, v99
	v_and_b32_e32 v59, 0xffff0000, v99
	v_pk_mul_f32 v[60:61], v[4:5], v[36:37]
	v_pk_mul_f32 v[62:63], v[6:7], v[38:39]
	v_pk_mul_f32 v[64:65], v[8:9], v[40:41]
	v_pk_mul_f32 v[66:67], v[10:11], v[42:43]
	v_pk_fma_f32 v[60:61], v[12:13], v[44:45], v[60:61]
	v_pk_fma_f32 v[62:63], v[14:15], v[46:47], v[62:63]
	v_pk_fma_f32 v[64:65], v[16:17], v[48:49], v[64:65]
	v_pk_fma_f32 v[66:67], v[18:19], v[50:51], v[66:67]
	v_pk_fma_f32 v[60:61], v[20:21], v[28:29], v[60:61]
	v_pk_fma_f32 v[62:63], v[22:23], v[30:31], v[62:63]
	v_pk_fma_f32 v[64:65], v[24:25], v[32:33], v[64:65]
	v_pk_fma_f32 v[66:67], v[26:27], v[34:35], v[66:67]
	v_pk_mul_f32 v[60:61], v[60:61], v[52:53]
	v_pk_mul_f32 v[62:63], v[62:63], v[54:55]
	v_pk_mul_f32 v[64:65], v[64:65], v[56:57]
	v_pk_mul_f32 v[66:67], v[66:67], v[58:59]
	v_cvt_pk_bf16_f32 v92, v60, v61
	v_cvt_pk_bf16_f32 v93, v62, v63
	v_cvt_pk_bf16_f32 v94, v64, v65
	v_cvt_pk_bf16_f32 v95, v66, v67
	global_store_dwordx4 v2, v[92:95], s[20:21]
	s_add_u32 s20, s20, 0x1000
	s_addc_u32 s21, s21, 0
	s_add_i32 s11, s11, 1
	s_cmp_eq_u32 s11, 0x1010
	s_cselect_b32 s11, 0, s11
	global_load_dwordx4 v[92:95], v2, s[18:19]
	global_load_dwordx4 v[96:99], v2, s[16:17]
	s_add_u32 s18, s18, 0x1000
	s_addc_u32 s19, s19, 0
	s_add_u32 s16, s16, 0x1000
	s_addc_u32 s17, s17, 0
	s_waitcnt vmcnt(24)
	s_cmp_eq_u32 s11, 0
	s_cbranch_scc0 .Lconv_nz4
	v_mov_b32_e32 v28, 0
	v_mov_b32_e32 v29, 0
	v_mov_b32_e32 v30, 0
	v_mov_b32_e32 v31, 0
	v_mov_b32_e32 v32, 0
	v_mov_b32_e32 v33, 0
	v_mov_b32_e32 v34, 0
	v_mov_b32_e32 v35, 0
	v_mov_b32_e32 v44, 0
	v_mov_b32_e32 v45, 0
	v_mov_b32_e32 v46, 0
	v_mov_b32_e32 v47, 0
	v_mov_b32_e32 v48, 0
	v_mov_b32_e32 v49, 0
	v_mov_b32_e32 v50, 0
	v_mov_b32_e32 v51, 0
.Lconv_nz4:
	v_lshlrev_b32_e32 v36, 16, v100
	v_and_b32_e32 v37, 0xffff0000, v100
	v_lshlrev_b32_e32 v38, 16, v101
	v_and_b32_e32 v39, 0xffff0000, v101
	v_lshlrev_b32_e32 v40, 16, v102
	v_and_b32_e32 v41, 0xffff0000, v102
	v_lshlrev_b32_e32 v42, 16, v103
	v_and_b32_e32 v43, 0xffff0000, v103
	v_lshlrev_b32_e32 v52, 16, v104
	v_and_b32_e32 v53, 0xffff0000, v104
	v_lshlrev_b32_e32 v54, 16, v105
	v_and_b32_e32 v55, 0xffff0000, v105
	v_lshlrev_b32_e32 v56, 16, v106
	v_and_b32_e32 v57, 0xffff0000, v106
	v_lshlrev_b32_e32 v58, 16, v107
	v_and_b32_e32 v59, 0xffff0000, v107
	v_pk_mul_f32 v[60:61], v[4:5], v[44:45]
	v_pk_mul_f32 v[62:63], v[6:7], v[46:47]
	v_pk_mul_f32 v[64:65], v[8:9], v[48:49]
	v_pk_mul_f32 v[66:67], v[10:11], v[50:51]
	v_pk_fma_f32 v[60:61], v[12:13], v[28:29], v[60:61]
	v_pk_fma_f32 v[62:63], v[14:15], v[30:31], v[62:63]
	v_pk_fma_f32 v[64:65], v[16:17], v[32:33], v[64:65]
	v_pk_fma_f32 v[66:67], v[18:19], v[34:35], v[66:67]
	v_pk_fma_f32 v[60:61], v[20:21], v[36:37], v[60:61]
	v_pk_fma_f32 v[62:63], v[22:23], v[38:39], v[62:63]
	v_pk_fma_f32 v[64:65], v[24:25], v[40:41], v[64:65]
	v_pk_fma_f32 v[66:67], v[26:27], v[42:43], v[66:67]
	v_pk_mul_f32 v[60:61], v[60:61], v[52:53]
	v_pk_mul_f32 v[62:63], v[62:63], v[54:55]
	v_pk_mul_f32 v[64:65], v[64:65], v[56:57]
	v_pk_mul_f32 v[66:67], v[66:67], v[58:59]
	v_cvt_pk_bf16_f32 v100, v60, v61
	v_cvt_pk_bf16_f32 v101, v62, v63
	v_cvt_pk_bf16_f32 v102, v64, v65
	v_cvt_pk_bf16_f32 v103, v66, v67
	global_store_dwordx4 v2, v[100:103], s[20:21]
	s_add_u32 s20, s20, 0x1000
	s_addc_u32 s21, s21, 0
	s_add_i32 s11, s11, 1
	s_cmp_eq_u32 s11, 0x1010
	s_cselect_b32 s11, 0, s11
	global_load_dwordx4 v[100:103], v2, s[18:19]
	global_load_dwordx4 v[104:107], v2, s[16:17]
	s_add_u32 s18, s18, 0x1000
	s_addc_u32 s19, s19, 0
	s_add_u32 s16, s16, 0x1000
	s_addc_u32 s17, s17, 0
	s_waitcnt vmcnt(25)
	s_cmp_eq_u32 s11, 0
	s_cbranch_scc0 .Lconv_nz5
	v_mov_b32_e32 v36, 0
	v_mov_b32_e32 v37, 0
	v_mov_b32_e32 v38, 0
	v_mov_b32_e32 v39, 0
	v_mov_b32_e32 v40, 0
	v_mov_b32_e32 v41, 0
	v_mov_b32_e32 v42, 0
	v_mov_b32_e32 v43, 0
	v_mov_b32_e32 v28, 0
	v_mov_b32_e32 v29, 0
	v_mov_b32_e32 v30, 0
	v_mov_b32_e32 v31, 0
	v_mov_b32_e32 v32, 0
	v_mov_b32_e32 v33, 0
	v_mov_b32_e32 v34, 0
	v_mov_b32_e32 v35, 0
.Lconv_nz5:
	v_lshlrev_b32_e32 v44, 16, v108
	v_and_b32_e32 v45, 0xffff0000, v108
	v_lshlrev_b32_e32 v46, 16, v109
	v_and_b32_e32 v47, 0xffff0000, v109
	v_lshlrev_b32_e32 v48, 16, v110
	v_and_b32_e32 v49, 0xffff0000, v110
	v_lshlrev_b32_e32 v50, 16, v111
	v_and_b32_e32 v51, 0xffff0000, v111
	v_lshlrev_b32_e32 v52, 16, v112
	v_and_b32_e32 v53, 0xffff0000, v112
	v_lshlrev_b32_e32 v54, 16, v113
	v_and_b32_e32 v55, 0xffff0000, v113
	v_lshlrev_b32_e32 v56, 16, v114
	v_and_b32_e32 v57, 0xffff0000, v114
	v_lshlrev_b32_e32 v58, 16, v115
	v_and_b32_e32 v59, 0xffff0000, v115
	v_pk_mul_f32 v[60:61], v[4:5], v[28:29]
	v_pk_mul_f32 v[62:63], v[6:7], v[30:31]
	v_pk_mul_f32 v[64:65], v[8:9], v[32:33]
	v_pk_mul_f32 v[66:67], v[10:11], v[34:35]
	v_pk_fma_f32 v[60:61], v[12:13], v[36:37], v[60:61]
	v_pk_fma_f32 v[62:63], v[14:15], v[38:39], v[62:63]
	v_pk_fma_f32 v[64:65], v[16:17], v[40:41], v[64:65]
	v_pk_fma_f32 v[66:67], v[18:19], v[42:43], v[66:67]
	v_pk_fma_f32 v[60:61], v[20:21], v[44:45], v[60:61]
	v_pk_fma_f32 v[62:63], v[22:23], v[46:47], v[62:63]
	v_pk_fma_f32 v[64:65], v[24:25], v[48:49], v[64:65]
	v_pk_fma_f32 v[66:67], v[26:27], v[50:51], v[66:67]
	v_pk_mul_f32 v[60:61], v[60:61], v[52:53]
	v_pk_mul_f32 v[62:63], v[62:63], v[54:55]
	v_pk_mul_f32 v[64:65], v[64:65], v[56:57]
	v_pk_mul_f32 v[66:67], v[66:67], v[58:59]
	v_cvt_pk_bf16_f32 v108, v60, v61
	v_cvt_pk_bf16_f32 v109, v62, v63
	v_cvt_pk_bf16_f32 v110, v64, v65
	v_cvt_pk_bf16_f32 v111, v66, v67
	global_store_dwordx4 v2, v[108:111], s[20:21]
	s_add_u32 s20, s20, 0x1000
	s_addc_u32 s21, s21, 0
	s_add_i32 s11, s11, 1
	s_cmp_eq_u32 s11, 0x1010
	s_cselect_b32 s11, 0, s11
	global_load_dwordx4 v[108:111], v2, s[18:19]
	global_load_dwordx4 v[112:115], v2, s[16:17]
	s_add_u32 s18, s18, 0x1000
	s_addc_u32 s19, s19, 0
	s_add_u32 s16, s16, 0x1000
	s_addc_u32 s17, s17, 0
	s_waitcnt vmcnt(26)
	s_cmp_eq_u32 s11, 0
	s_cbranch_scc0 .Lconv_nz6
	v_mov_b32_e32 v44, 0
	v_mov_b32_e32 v45, 0
	v_mov_b32_e32 v46, 0
	v_mov_b32_e32 v47, 0
	v_mov_b32_e32 v48, 0
	v_mov_b32_e32 v49, 0
	v_mov_b32_e32 v50, 0
	v_mov_b32_e32 v51, 0
	v_mov_b32_e32 v36, 0
	v_mov_b32_e32 v37, 0
	v_mov_b32_e32 v38, 0
	v_mov_b32_e32 v39, 0
	v_mov_b32_e32 v40, 0
	v_mov_b32_e32 v41, 0
	v_mov_b32_e32 v42, 0
	v_mov_b32_e32 v43, 0
.Lconv_nz6:
	v_lshlrev_b32_e32 v28, 16, v116
	v_and_b32_e32 v29, 0xffff0000, v116
	v_lshlrev_b32_e32 v30, 16, v117
	v_and_b32_e32 v31, 0xffff0000, v117
	v_lshlrev_b32_e32 v32, 16, v118
	v_and_b32_e32 v33, 0xffff0000, v118
	v_lshlrev_b32_e32 v34, 16, v119
	v_and_b32_e32 v35, 0xffff0000, v119
	v_lshlrev_b32_e32 v52, 16, v120
	v_and_b32_e32 v53, 0xffff0000, v120
	v_lshlrev_b32_e32 v54, 16, v121
	v_and_b32_e32 v55, 0xffff0000, v121
	v_lshlrev_b32_e32 v56, 16, v122
	v_and_b32_e32 v57, 0xffff0000, v122
	v_lshlrev_b32_e32 v58, 16, v123
	v_and_b32_e32 v59, 0xffff0000, v123
	v_pk_mul_f32 v[60:61], v[4:5], v[36:37]
	v_pk_mul_f32 v[62:63], v[6:7], v[38:39]
	v_pk_mul_f32 v[64:65], v[8:9], v[40:41]
	v_pk_mul_f32 v[66:67], v[10:11], v[42:43]
	v_pk_fma_f32 v[60:61], v[12:13], v[44:45], v[60:61]
	v_pk_fma_f32 v[62:63], v[14:15], v[46:47], v[62:63]
	v_pk_fma_f32 v[64:65], v[16:17], v[48:49], v[64:65]
	v_pk_fma_f32 v[66:67], v[18:19], v[50:51], v[66:67]
	v_pk_fma_f32 v[60:61], v[20:21], v[28:29], v[60:61]
	v_pk_fma_f32 v[62:63], v[22:23], v[30:31], v[62:63]
	v_pk_fma_f32 v[64:65], v[24:25], v[32:33], v[64:65]
	v_pk_fma_f32 v[66:67], v[26:27], v[34:35], v[66:67]
	v_pk_mul_f32 v[60:61], v[60:61], v[52:53]
	v_pk_mul_f32 v[62:63], v[62:63], v[54:55]
	v_pk_mul_f32 v[64:65], v[64:65], v[56:57]
	v_pk_mul_f32 v[66:67], v[66:67], v[58:59]
	v_cvt_pk_bf16_f32 v116, v60, v61
	v_cvt_pk_bf16_f32 v117, v62, v63
	v_cvt_pk_bf16_f32 v118, v64, v65
	v_cvt_pk_bf16_f32 v119, v66, v67
	global_store_dwordx4 v2, v[116:119], s[20:21]
	s_add_u32 s20, s20, 0x1000
	s_addc_u32 s21, s21, 0
	s_add_i32 s11, s11, 1
	s_cmp_eq_u32 s11, 0x1010
	s_cselect_b32 s11, 0, s11
	global_load_dwordx4 v[116:119], v2, s[18:19]
	global_load_dwordx4 v[120:123], v2, s[16:17]
	s_add_u32 s18, s18, 0x1000
	s_addc_u32 s19, s19, 0
	s_add_u32 s16, s16, 0x1000
	s_addc_u32 s17, s17, 0
	s_waitcnt vmcnt(27)
	s_cmp_eq_u32 s11, 0
	s_cbranch_scc0 .Lconv_nz7
	v_mov_b32_e32 v28, 0
	v_mov_b32_e32 v29, 0
	v_mov_b32_e32 v30, 0
	v_mov_b32_e32 v31, 0
	v_mov_b32_e32 v32, 0
	v_mov_b32_e32 v33, 0
	v_mov_b32_e32 v34, 0
	v_mov_b32_e32 v35, 0
	v_mov_b32_e32 v44, 0
	v_mov_b32_e32 v45, 0
	v_mov_b32_e32 v46, 0
	v_mov_b32_e32 v47, 0
	v_mov_b32_e32 v48, 0
	v_mov_b32_e32 v49, 0
	v_mov_b32_e32 v50, 0
	v_mov_b32_e32 v51, 0
.Lconv_nz7:
	v_lshlrev_b32_e32 v36, 16, v132
	v_and_b32_e32 v37, 0xffff0000, v132
	v_lshlrev_b32_e32 v38, 16, v133
	v_and_b32_e32 v39, 0xffff0000, v133
	v_lshlrev_b32_e32 v40, 16, v134
	v_and_b32_e32 v41, 0xffff0000, v134
	v_lshlrev_b32_e32 v42, 16, v135
	v_and_b32_e32 v43, 0xffff0000, v135
	v_lshlrev_b32_e32 v52, 16, v136
	v_and_b32_e32 v53, 0xffff0000, v136
	v_lshlrev_b32_e32 v54, 16, v137
	v_and_b32_e32 v55, 0xffff0000, v137
	v_lshlrev_b32_e32 v56, 16, v138
	v_and_b32_e32 v57, 0xffff0000, v138
	v_lshlrev_b32_e32 v58, 16, v139
	v_and_b32_e32 v59, 0xffff0000, v139
	v_pk_mul_f32 v[60:61], v[4:5], v[44:45]
	v_pk_mul_f32 v[62:63], v[6:7], v[46:47]
	v_pk_mul_f32 v[64:65], v[8:9], v[48:49]
	v_pk_mul_f32 v[66:67], v[10:11], v[50:51]
	v_pk_fma_f32 v[60:61], v[12:13], v[28:29], v[60:61]
	v_pk_fma_f32 v[62:63], v[14:15], v[30:31], v[62:63]
	v_pk_fma_f32 v[64:65], v[16:17], v[32:33], v[64:65]
	v_pk_fma_f32 v[66:67], v[18:19], v[34:35], v[66:67]
	v_pk_fma_f32 v[60:61], v[20:21], v[36:37], v[60:61]
	v_pk_fma_f32 v[62:63], v[22:23], v[38:39], v[62:63]
	v_pk_fma_f32 v[64:65], v[24:25], v[40:41], v[64:65]
	v_pk_fma_f32 v[66:67], v[26:27], v[42:43], v[66:67]
	v_pk_mul_f32 v[60:61], v[60:61], v[52:53]
	v_pk_mul_f32 v[62:63], v[62:63], v[54:55]
	v_pk_mul_f32 v[64:65], v[64:65], v[56:57]
	v_pk_mul_f32 v[66:67], v[66:67], v[58:59]
	v_cvt_pk_bf16_f32 v132, v60, v61
	v_cvt_pk_bf16_f32 v133, v62, v63
	v_cvt_pk_bf16_f32 v134, v64, v65
	v_cvt_pk_bf16_f32 v135, v66, v67
	global_store_dwordx4 v2, v[132:135], s[20:21]
	s_add_u32 s20, s20, 0x1000
	s_addc_u32 s21, s21, 0
	s_add_i32 s11, s11, 1
	s_cmp_eq_u32 s11, 0x1010
	s_cselect_b32 s11, 0, s11
	global_load_dwordx4 v[132:135], v2, s[18:19]
	global_load_dwordx4 v[136:139], v2, s[16:17]
	s_add_u32 s18, s18, 0x1000
	s_addc_u32 s19, s19, 0
	s_add_u32 s16, s16, 0x1000
	s_addc_u32 s17, s17, 0
	s_waitcnt vmcnt(28)
	s_cmp_eq_u32 s11, 0
	s_cbranch_scc0 .Lconv_nz8
	v_mov_b32_e32 v36, 0
	v_mov_b32_e32 v37, 0
	v_mov_b32_e32 v38, 0
	v_mov_b32_e32 v39, 0
	v_mov_b32_e32 v40, 0
	v_mov_b32_e32 v41, 0
	v_mov_b32_e32 v42, 0
	v_mov_b32_e32 v43, 0
	v_mov_b32_e32 v28, 0
	v_mov_b32_e32 v29, 0
	v_mov_b32_e32 v30, 0
	v_mov_b32_e32 v31, 0
	v_mov_b32_e32 v32, 0
	v_mov_b32_e32 v33, 0
	v_mov_b32_e32 v34, 0
	v_mov_b32_e32 v35, 0
.Lconv_nz8:
	v_lshlrev_b32_e32 v44, 16, v140
	v_and_b32_e32 v45, 0xffff0000, v140
	v_lshlrev_b32_e32 v46, 16, v141
	v_and_b32_e32 v47, 0xffff0000, v141
	v_lshlrev_b32_e32 v48, 16, v142
	v_and_b32_e32 v49, 0xffff0000, v142
	v_lshlrev_b32_e32 v50, 16, v143
	v_and_b32_e32 v51, 0xffff0000, v143
	v_lshlrev_b32_e32 v52, 16, v144
	v_and_b32_e32 v53, 0xffff0000, v144
	v_lshlrev_b32_e32 v54, 16, v145
	v_and_b32_e32 v55, 0xffff0000, v145
	v_lshlrev_b32_e32 v56, 16, v146
	v_and_b32_e32 v57, 0xffff0000, v146
	v_lshlrev_b32_e32 v58, 16, v147
	v_and_b32_e32 v59, 0xffff0000, v147
	v_pk_mul_f32 v[60:61], v[4:5], v[28:29]
	v_pk_mul_f32 v[62:63], v[6:7], v[30:31]
	v_pk_mul_f32 v[64:65], v[8:9], v[32:33]
	v_pk_mul_f32 v[66:67], v[10:11], v[34:35]
	v_pk_fma_f32 v[60:61], v[12:13], v[36:37], v[60:61]
	v_pk_fma_f32 v[62:63], v[14:15], v[38:39], v[62:63]
	v_pk_fma_f32 v[64:65], v[16:17], v[40:41], v[64:65]
	v_pk_fma_f32 v[66:67], v[18:19], v[42:43], v[66:67]
	v_pk_fma_f32 v[60:61], v[20:21], v[44:45], v[60:61]
	v_pk_fma_f32 v[62:63], v[22:23], v[46:47], v[62:63]
	v_pk_fma_f32 v[64:65], v[24:25], v[48:49], v[64:65]
	v_pk_fma_f32 v[66:67], v[26:27], v[50:51], v[66:67]
	v_pk_mul_f32 v[60:61], v[60:61], v[52:53]
	v_pk_mul_f32 v[62:63], v[62:63], v[54:55]
	v_pk_mul_f32 v[64:65], v[64:65], v[56:57]
	v_pk_mul_f32 v[66:67], v[66:67], v[58:59]
	v_cvt_pk_bf16_f32 v140, v60, v61
	v_cvt_pk_bf16_f32 v141, v62, v63
	v_cvt_pk_bf16_f32 v142, v64, v65
	v_cvt_pk_bf16_f32 v143, v66, v67
	global_store_dwordx4 v2, v[140:143], s[20:21]
	s_add_u32 s20, s20, 0x1000
	s_addc_u32 s21, s21, 0
	s_add_i32 s11, s11, 1
	s_cmp_eq_u32 s11, 0x1010
	s_cselect_b32 s11, 0, s11
	global_load_dwordx4 v[140:143], v2, s[18:19]
	global_load_dwordx4 v[144:147], v2, s[16:17]
	s_add_u32 s18, s18, 0x1000
	s_addc_u32 s19, s19, 0
	s_add_u32 s16, s16, 0x1000
	s_addc_u32 s17, s17, 0
	s_waitcnt vmcnt(29)
	s_cmp_eq_u32 s11, 0
	s_cbranch_scc0 .Lconv_nz9
	v_mov_b32_e32 v44, 0
	v_mov_b32_e32 v45, 0
	v_mov_b32_e32 v46, 0
	v_mov_b32_e32 v47, 0
	v_mov_b32_e32 v48, 0
	v_mov_b32_e32 v49, 0
	v_mov_b32_e32 v50, 0
	v_mov_b32_e32 v51, 0
	v_mov_b32_e32 v36, 0
	v_mov_b32_e32 v37, 0
	v_mov_b32_e32 v38, 0
	v_mov_b32_e32 v39, 0
	v_mov_b32_e32 v40, 0
	v_mov_b32_e32 v41, 0
	v_mov_b32_e32 v42, 0
	v_mov_b32_e32 v43, 0
.Lconv_nz9:
	v_lshlrev_b32_e32 v28, 16, v148
	v_and_b32_e32 v29, 0xffff0000, v148
	v_lshlrev_b32_e32 v30, 16, v149
	v_and_b32_e32 v31, 0xffff0000, v149
	v_lshlrev_b32_e32 v32, 16, v150
	v_and_b32_e32 v33, 0xffff0000, v150
	v_lshlrev_b32_e32 v34, 16, v151
	v_and_b32_e32 v35, 0xffff0000, v151
	v_lshlrev_b32_e32 v52, 16, v152
	v_and_b32_e32 v53, 0xffff0000, v152
	v_lshlrev_b32_e32 v54, 16, v153
	v_and_b32_e32 v55, 0xffff0000, v153
	v_lshlrev_b32_e32 v56, 16, v154
	v_and_b32_e32 v57, 0xffff0000, v154
	v_lshlrev_b32_e32 v58, 16, v155
	v_and_b32_e32 v59, 0xffff0000, v155
	v_pk_mul_f32 v[60:61], v[4:5], v[36:37]
	v_pk_mul_f32 v[62:63], v[6:7], v[38:39]
	v_pk_mul_f32 v[64:65], v[8:9], v[40:41]
	v_pk_mul_f32 v[66:67], v[10:11], v[42:43]
	v_pk_fma_f32 v[60:61], v[12:13], v[44:45], v[60:61]
	v_pk_fma_f32 v[62:63], v[14:15], v[46:47], v[62:63]
	v_pk_fma_f32 v[64:65], v[16:17], v[48:49], v[64:65]
	v_pk_fma_f32 v[66:67], v[18:19], v[50:51], v[66:67]
	v_pk_fma_f32 v[60:61], v[20:21], v[28:29], v[60:61]
	v_pk_fma_f32 v[62:63], v[22:23], v[30:31], v[62:63]
	v_pk_fma_f32 v[64:65], v[24:25], v[32:33], v[64:65]
	v_pk_fma_f32 v[66:67], v[26:27], v[34:35], v[66:67]
	v_pk_mul_f32 v[60:61], v[60:61], v[52:53]
	v_pk_mul_f32 v[62:63], v[62:63], v[54:55]
	v_pk_mul_f32 v[64:65], v[64:65], v[56:57]
	v_pk_mul_f32 v[66:67], v[66:67], v[58:59]
	v_cvt_pk_bf16_f32 v148, v60, v61
	v_cvt_pk_bf16_f32 v149, v62, v63
	v_cvt_pk_bf16_f32 v150, v64, v65
	v_cvt_pk_bf16_f32 v151, v66, v67
	global_store_dwordx4 v2, v[148:151], s[20:21]
	s_add_u32 s20, s20, 0x1000
	s_addc_u32 s21, s21, 0
	s_add_i32 s11, s11, 1
	s_cmp_eq_u32 s11, 0x1010
	s_cselect_b32 s11, 0, s11
	global_load_dwordx4 v[148:151], v2, s[18:19]
	global_load_dwordx4 v[152:155], v2, s[16:17]
	s_add_u32 s18, s18, 0x1000
	s_addc_u32 s19, s19, 0
	s_add_u32 s16, s16, 0x1000
	s_addc_u32 s17, s17, 0
	s_waitcnt vmcnt(30)
	s_cmp_eq_u32 s11, 0
	s_cbranch_scc0 .Lconv_nz10
	v_mov_b32_e32 v28, 0
	v_mov_b32_e32 v29, 0
	v_mov_b32_e32 v30, 0
	v_mov_b32_e32 v31, 0
	v_mov_b32_e32 v32, 0
	v_mov_b32_e32 v33, 0
	v_mov_b32_e32 v34, 0
	v_mov_b32_e32 v35, 0
	v_mov_b32_e32 v44, 0
	v_mov_b32_e32 v45, 0
	v_mov_b32_e32 v46, 0
	v_mov_b32_e32 v47, 0
	v_mov_b32_e32 v48, 0
	v_mov_b32_e32 v49, 0
	v_mov_b32_e32 v50, 0
	v_mov_b32_e32 v51, 0
.Lconv_nz10:
	v_lshlrev_b32_e32 v36, 16, v156
	v_and_b32_e32 v37, 0xffff0000, v156
	v_lshlrev_b32_e32 v38, 16, v157
	v_and_b32_e32 v39, 0xffff0000, v157
	v_lshlrev_b32_e32 v40, 16, v158
	v_and_b32_e32 v41, 0xffff0000, v158
	v_lshlrev_b32_e32 v42, 16, v159
	v_and_b32_e32 v43, 0xffff0000, v159
	v_lshlrev_b32_e32 v52, 16, v160
	v_and_b32_e32 v53, 0xffff0000, v160
	v_lshlrev_b32_e32 v54, 16, v161
	v_and_b32_e32 v55, 0xffff0000, v161
	v_lshlrev_b32_e32 v56, 16, v162
	v_and_b32_e32 v57, 0xffff0000, v162
	v_lshlrev_b32_e32 v58, 16, v163
	v_and_b32_e32 v59, 0xffff0000, v163
	v_pk_mul_f32 v[60:61], v[4:5], v[44:45]
	v_pk_mul_f32 v[62:63], v[6:7], v[46:47]
	v_pk_mul_f32 v[64:65], v[8:9], v[48:49]
	v_pk_mul_f32 v[66:67], v[10:11], v[50:51]
	v_pk_fma_f32 v[60:61], v[12:13], v[28:29], v[60:61]
	v_pk_fma_f32 v[62:63], v[14:15], v[30:31], v[62:63]
	v_pk_fma_f32 v[64:65], v[16:17], v[32:33], v[64:65]
	v_pk_fma_f32 v[66:67], v[18:19], v[34:35], v[66:67]
	v_pk_fma_f32 v[60:61], v[20:21], v[36:37], v[60:61]
	v_pk_fma_f32 v[62:63], v[22:23], v[38:39], v[62:63]
	v_pk_fma_f32 v[64:65], v[24:25], v[40:41], v[64:65]
	v_pk_fma_f32 v[66:67], v[26:27], v[42:43], v[66:67]
	v_pk_mul_f32 v[60:61], v[60:61], v[52:53]
	v_pk_mul_f32 v[62:63], v[62:63], v[54:55]
	v_pk_mul_f32 v[64:65], v[64:65], v[56:57]
	v_pk_mul_f32 v[66:67], v[66:67], v[58:59]
	v_cvt_pk_bf16_f32 v156, v60, v61
	v_cvt_pk_bf16_f32 v157, v62, v63
	v_cvt_pk_bf16_f32 v158, v64, v65
	v_cvt_pk_bf16_f32 v159, v66, v67
	global_store_dwordx4 v2, v[156:159], s[20:21]
	s_add_u32 s20, s20, 0x1000
	s_addc_u32 s21, s21, 0
	s_add_i32 s11, s11, 1
	s_cmp_eq_u32 s11, 0x1010
	s_cselect_b32 s11, 0, s11
	global_load_dwordx4 v[156:159], v2, s[18:19]
	global_load_dwordx4 v[160:163], v2, s[16:17]
	s_add_u32 s18, s18, 0x1000
	s_addc_u32 s19, s19, 0
	s_add_u32 s16, s16, 0x1000
	s_addc_u32 s17, s17, 0
	s_waitcnt vmcnt(30)
	s_cmp_eq_u32 s11, 0
	s_cbranch_scc0 .Lconv_nz11
	v_mov_b32_e32 v36, 0
	v_mov_b32_e32 v37, 0
	v_mov_b32_e32 v38, 0
	v_mov_b32_e32 v39, 0
	v_mov_b32_e32 v40, 0
	v_mov_b32_e32 v41, 0
	v_mov_b32_e32 v42, 0
	v_mov_b32_e32 v43, 0
	v_mov_b32_e32 v28, 0
	v_mov_b32_e32 v29, 0
	v_mov_b32_e32 v30, 0
	v_mov_b32_e32 v31, 0
	v_mov_b32_e32 v32, 0
	v_mov_b32_e32 v33, 0
	v_mov_b32_e32 v34, 0
	v_mov_b32_e32 v35, 0
.Lconv_nz11:
	v_lshlrev_b32_e32 v44, 16, v68
	v_and_b32_e32 v45, 0xffff0000, v68
	v_lshlrev_b32_e32 v46, 16, v69
	v_and_b32_e32 v47, 0xffff0000, v69
	v_lshlrev_b32_e32 v48, 16, v70
	v_and_b32_e32 v49, 0xffff0000, v70
	v_lshlrev_b32_e32 v50, 16, v71
	v_and_b32_e32 v51, 0xffff0000, v71
	v_lshlrev_b32_e32 v52, 16, v72
	v_and_b32_e32 v53, 0xffff0000, v72
	v_lshlrev_b32_e32 v54, 16, v73
	v_and_b32_e32 v55, 0xffff0000, v73
	v_lshlrev_b32_e32 v56, 16, v74
	v_and_b32_e32 v57, 0xffff0000, v74
	v_lshlrev_b32_e32 v58, 16, v75
	v_and_b32_e32 v59, 0xffff0000, v75
	v_pk_mul_f32 v[60:61], v[4:5], v[28:29]
	v_pk_mul_f32 v[62:63], v[6:7], v[30:31]
	v_pk_mul_f32 v[64:65], v[8:9], v[32:33]
	v_pk_mul_f32 v[66:67], v[10:11], v[34:35]
	v_pk_fma_f32 v[60:61], v[12:13], v[36:37], v[60:61]
	v_pk_fma_f32 v[62:63], v[14:15], v[38:39], v[62:63]
	v_pk_fma_f32 v[64:65], v[16:17], v[40:41], v[64:65]
	v_pk_fma_f32 v[66:67], v[18:19], v[42:43], v[66:67]
	v_pk_fma_f32 v[60:61], v[20:21], v[44:45], v[60:61]
	v_pk_fma_f32 v[62:63], v[22:23], v[46:47], v[62:63]
	v_pk_fma_f32 v[64:65], v[24:25], v[48:49], v[64:65]
	v_pk_fma_f32 v[66:67], v[26:27], v[50:51], v[66:67]
	v_pk_mul_f32 v[60:61], v[60:61], v[52:53]
	v_pk_mul_f32 v[62:63], v[62:63], v[54:55]
	v_pk_mul_f32 v[64:65], v[64:65], v[56:57]
	v_pk_mul_f32 v[66:67], v[66:67], v[58:59]
	v_cvt_pk_bf16_f32 v68, v60, v61
	v_cvt_pk_bf16_f32 v69, v62, v63
	v_cvt_pk_bf16_f32 v70, v64, v65
	v_cvt_pk_bf16_f32 v71, v66, v67
	global_store_dwordx4 v2, v[68:71], s[20:21]
	s_add_u32 s20, s20, 0x1000
	s_addc_u32 s21, s21, 0
	s_add_i32 s11, s11, 1
	s_cmp_eq_u32 s11, 0x1010
	s_cselect_b32 s11, 0, s11
	global_load_dwordx4 v[68:71], v2, s[18:19]
	global_load_dwordx4 v[72:75], v2, s[16:17]
	s_add_u32 s18, s18, 0x1000
	s_addc_u32 s19, s19, 0
	s_add_u32 s16, s16, 0x1000
	s_addc_u32 s17, s17, 0
	s_waitcnt vmcnt(30)
	s_cmp_eq_u32 s11, 0
	s_cbranch_scc0 .Lconv_nz12
	v_mov_b32_e32 v44, 0
	v_mov_b32_e32 v45, 0
	v_mov_b32_e32 v46, 0
	v_mov_b32_e32 v47, 0
	v_mov_b32_e32 v48, 0
	v_mov_b32_e32 v49, 0
	v_mov_b32_e32 v50, 0
	v_mov_b32_e32 v51, 0
	v_mov_b32_e32 v36, 0
	v_mov_b32_e32 v37, 0
	v_mov_b32_e32 v38, 0
	v_mov_b32_e32 v39, 0
	v_mov_b32_e32 v40, 0
	v_mov_b32_e32 v41, 0
	v_mov_b32_e32 v42, 0
	v_mov_b32_e32 v43, 0
.Lconv_nz12:
	v_lshlrev_b32_e32 v28, 16, v76
	v_and_b32_e32 v29, 0xffff0000, v76
	v_lshlrev_b32_e32 v30, 16, v77
	v_and_b32_e32 v31, 0xffff0000, v77
	v_lshlrev_b32_e32 v32, 16, v78
	v_and_b32_e32 v33, 0xffff0000, v78
	v_lshlrev_b32_e32 v34, 16, v79
	v_and_b32_e32 v35, 0xffff0000, v79
	v_lshlrev_b32_e32 v52, 16, v80
	v_and_b32_e32 v53, 0xffff0000, v80
	v_lshlrev_b32_e32 v54, 16, v81
	v_and_b32_e32 v55, 0xffff0000, v81
	v_lshlrev_b32_e32 v56, 16, v82
	v_and_b32_e32 v57, 0xffff0000, v82
	v_lshlrev_b32_e32 v58, 16, v83
	v_and_b32_e32 v59, 0xffff0000, v83
	v_pk_mul_f32 v[60:61], v[4:5], v[36:37]
	v_pk_mul_f32 v[62:63], v[6:7], v[38:39]
	v_pk_mul_f32 v[64:65], v[8:9], v[40:41]
	v_pk_mul_f32 v[66:67], v[10:11], v[42:43]
	v_pk_fma_f32 v[60:61], v[12:13], v[44:45], v[60:61]
	v_pk_fma_f32 v[62:63], v[14:15], v[46:47], v[62:63]
	v_pk_fma_f32 v[64:65], v[16:17], v[48:49], v[64:65]
	v_pk_fma_f32 v[66:67], v[18:19], v[50:51], v[66:67]
	v_pk_fma_f32 v[60:61], v[20:21], v[28:29], v[60:61]
	v_pk_fma_f32 v[62:63], v[22:23], v[30:31], v[62:63]
	v_pk_fma_f32 v[64:65], v[24:25], v[32:33], v[64:65]
	v_pk_fma_f32 v[66:67], v[26:27], v[34:35], v[66:67]
	v_pk_mul_f32 v[60:61], v[60:61], v[52:53]
	v_pk_mul_f32 v[62:63], v[62:63], v[54:55]
	v_pk_mul_f32 v[64:65], v[64:65], v[56:57]
	v_pk_mul_f32 v[66:67], v[66:67], v[58:59]
	v_cvt_pk_bf16_f32 v76, v60, v61
	v_cvt_pk_bf16_f32 v77, v62, v63
	v_cvt_pk_bf16_f32 v78, v64, v65
	v_cvt_pk_bf16_f32 v79, v66, v67
	global_store_dwordx4 v2, v[76:79], s[20:21]
	s_add_u32 s20, s20, 0x1000
	s_addc_u32 s21, s21, 0
	s_add_i32 s11, s11, 1
	s_cmp_eq_u32 s11, 0x1010
	s_cselect_b32 s11, 0, s11
	global_load_dwordx4 v[76:79], v2, s[18:19]
	global_load_dwordx4 v[80:83], v2, s[16:17]
	s_add_u32 s18, s18, 0x1000
	s_addc_u32 s19, s19, 0
	s_add_u32 s16, s16, 0x1000
	s_addc_u32 s17, s17, 0
	s_waitcnt vmcnt(30)
	s_cmp_eq_u32 s11, 0
	s_cbranch_scc0 .Lconv_nz13
	v_mov_b32_e32 v28, 0
	v_mov_b32_e32 v29, 0
	v_mov_b32_e32 v30, 0
	v_mov_b32_e32 v31, 0
	v_mov_b32_e32 v32, 0
	v_mov_b32_e32 v33, 0
	v_mov_b32_e32 v34, 0
	v_mov_b32_e32 v35, 0
	v_mov_b32_e32 v44, 0
	v_mov_b32_e32 v45, 0
	v_mov_b32_e32 v46, 0
	v_mov_b32_e32 v47, 0
	v_mov_b32_e32 v48, 0
	v_mov_b32_e32 v49, 0
	v_mov_b32_e32 v50, 0
	v_mov_b32_e32 v51, 0
.Lconv_nz13:
	v_lshlrev_b32_e32 v36, 16, v84
	v_and_b32_e32 v37, 0xffff0000, v84
	v_lshlrev_b32_e32 v38, 16, v85
	v_and_b32_e32 v39, 0xffff0000, v85
	v_lshlrev_b32_e32 v40, 16, v86
	v_and_b32_e32 v41, 0xffff0000, v86
	v_lshlrev_b32_e32 v42, 16, v87
	v_and_b32_e32 v43, 0xffff0000, v87
	v_lshlrev_b32_e32 v52, 16, v88
	v_and_b32_e32 v53, 0xffff0000, v88
	v_lshlrev_b32_e32 v54, 16, v89
	v_and_b32_e32 v55, 0xffff0000, v89
	v_lshlrev_b32_e32 v56, 16, v90
	v_and_b32_e32 v57, 0xffff0000, v90
	v_lshlrev_b32_e32 v58, 16, v91
	v_and_b32_e32 v59, 0xffff0000, v91
	v_pk_mul_f32 v[60:61], v[4:5], v[44:45]
	v_pk_mul_f32 v[62:63], v[6:7], v[46:47]
	v_pk_mul_f32 v[64:65], v[8:9], v[48:49]
	v_pk_mul_f32 v[66:67], v[10:11], v[50:51]
	v_pk_fma_f32 v[60:61], v[12:13], v[28:29], v[60:61]
	v_pk_fma_f32 v[62:63], v[14:15], v[30:31], v[62:63]
	v_pk_fma_f32 v[64:65], v[16:17], v[32:33], v[64:65]
	v_pk_fma_f32 v[66:67], v[18:19], v[34:35], v[66:67]
	v_pk_fma_f32 v[60:61], v[20:21], v[36:37], v[60:61]
	v_pk_fma_f32 v[62:63], v[22:23], v[38:39], v[62:63]
	v_pk_fma_f32 v[64:65], v[24:25], v[40:41], v[64:65]
	v_pk_fma_f32 v[66:67], v[26:27], v[42:43], v[66:67]
	v_pk_mul_f32 v[60:61], v[60:61], v[52:53]
	v_pk_mul_f32 v[62:63], v[62:63], v[54:55]
	v_pk_mul_f32 v[64:65], v[64:65], v[56:57]
	v_pk_mul_f32 v[66:67], v[66:67], v[58:59]
	v_cvt_pk_bf16_f32 v84, v60, v61
	v_cvt_pk_bf16_f32 v85, v62, v63
	v_cvt_pk_bf16_f32 v86, v64, v65
	v_cvt_pk_bf16_f32 v87, v66, v67
	global_store_dwordx4 v2, v[84:87], s[20:21]
	s_add_u32 s20, s20, 0x1000
	s_addc_u32 s21, s21, 0
	s_add_i32 s11, s11, 1
	s_cmp_eq_u32 s11, 0x1010
	s_cselect_b32 s11, 0, s11
	global_load_dwordx4 v[84:87], v2, s[18:19]
	global_load_dwordx4 v[88:91], v2, s[16:17]
	s_add_u32 s18, s18, 0x1000
	s_addc_u32 s19, s19, 0
	s_add_u32 s16, s16, 0x1000
	s_addc_u32 s17, s17, 0
	s_waitcnt vmcnt(30)
	s_cmp_eq_u32 s11, 0
	s_cbranch_scc0 .Lconv_nz14
	v_mov_b32_e32 v36, 0
	v_mov_b32_e32 v37, 0
	v_mov_b32_e32 v38, 0
	v_mov_b32_e32 v39, 0
	v_mov_b32_e32 v40, 0
	v_mov_b32_e32 v41, 0
	v_mov_b32_e32 v42, 0
	v_mov_b32_e32 v43, 0
	v_mov_b32_e32 v28, 0
	v_mov_b32_e32 v29, 0
	v_mov_b32_e32 v30, 0
	v_mov_b32_e32 v31, 0
	v_mov_b32_e32 v32, 0
	v_mov_b32_e32 v33, 0
	v_mov_b32_e32 v34, 0
	v_mov_b32_e32 v35, 0
.Lconv_nz14:
	v_lshlrev_b32_e32 v44, 16, v92
	v_and_b32_e32 v45, 0xffff0000, v92
	v_lshlrev_b32_e32 v46, 16, v93
	v_and_b32_e32 v47, 0xffff0000, v93
	v_lshlrev_b32_e32 v48, 16, v94
	v_and_b32_e32 v49, 0xffff0000, v94
	v_lshlrev_b32_e32 v50, 16, v95
	v_and_b32_e32 v51, 0xffff0000, v95
	v_lshlrev_b32_e32 v52, 16, v96
	v_and_b32_e32 v53, 0xffff0000, v96
	v_lshlrev_b32_e32 v54, 16, v97
	v_and_b32_e32 v55, 0xffff0000, v97
	v_lshlrev_b32_e32 v56, 16, v98
	v_and_b32_e32 v57, 0xffff0000, v98
	v_lshlrev_b32_e32 v58, 16, v99
	v_and_b32_e32 v59, 0xffff0000, v99
	v_pk_mul_f32 v[60:61], v[4:5], v[28:29]
	v_pk_mul_f32 v[62:63], v[6:7], v[30:31]
	v_pk_mul_f32 v[64:65], v[8:9], v[32:33]
	v_pk_mul_f32 v[66:67], v[10:11], v[34:35]
	v_pk_fma_f32 v[60:61], v[12:13], v[36:37], v[60:61]
	v_pk_fma_f32 v[62:63], v[14:15], v[38:39], v[62:63]
	v_pk_fma_f32 v[64:65], v[16:17], v[40:41], v[64:65]
	v_pk_fma_f32 v[66:67], v[18:19], v[42:43], v[66:67]
	v_pk_fma_f32 v[60:61], v[20:21], v[44:45], v[60:61]
	v_pk_fma_f32 v[62:63], v[22:23], v[46:47], v[62:63]
	v_pk_fma_f32 v[64:65], v[24:25], v[48:49], v[64:65]
	v_pk_fma_f32 v[66:67], v[26:27], v[50:51], v[66:67]
	v_pk_mul_f32 v[60:61], v[60:61], v[52:53]
	v_pk_mul_f32 v[62:63], v[62:63], v[54:55]
	v_pk_mul_f32 v[64:65], v[64:65], v[56:57]
	v_pk_mul_f32 v[66:67], v[66:67], v[58:59]
	v_cvt_pk_bf16_f32 v92, v60, v61
	v_cvt_pk_bf16_f32 v93, v62, v63
	v_cvt_pk_bf16_f32 v94, v64, v65
	v_cvt_pk_bf16_f32 v95, v66, v67
	global_store_dwordx4 v2, v[92:95], s[20:21]
	s_add_u32 s20, s20, 0x1000
	s_addc_u32 s21, s21, 0
	s_add_i32 s11, s11, 1
	s_cmp_eq_u32 s11, 0x1010
	s_cselect_b32 s11, 0, s11
	global_load_dwordx4 v[92:95], v2, s[18:19]
	global_load_dwordx4 v[96:99], v2, s[16:17]
	s_add_u32 s18, s18, 0x1000
	s_addc_u32 s19, s19, 0
	s_add_u32 s16, s16, 0x1000
	s_addc_u32 s17, s17, 0
	s_waitcnt vmcnt(30)
	s_cmp_eq_u32 s11, 0
	s_cbranch_scc0 .Lconv_nz15
	v_mov_b32_e32 v44, 0
	v_mov_b32_e32 v45, 0
	v_mov_b32_e32 v46, 0
	v_mov_b32_e32 v47, 0
	v_mov_b32_e32 v48, 0
	v_mov_b32_e32 v49, 0
	v_mov_b32_e32 v50, 0
	v_mov_b32_e32 v51, 0
	v_mov_b32_e32 v36, 0
	v_mov_b32_e32 v37, 0
	v_mov_b32_e32 v38, 0
	v_mov_b32_e32 v39, 0
	v_mov_b32_e32 v40, 0
	v_mov_b32_e32 v41, 0
	v_mov_b32_e32 v42, 0
	v_mov_b32_e32 v43, 0
.Lconv_nz15:
	v_lshlrev_b32_e32 v28, 16, v100
	v_and_b32_e32 v29, 0xffff0000, v100
	v_lshlrev_b32_e32 v30, 16, v101
	v_and_b32_e32 v31, 0xffff0000, v101
	v_lshlrev_b32_e32 v32, 16, v102
	v_and_b32_e32 v33, 0xffff0000, v102
	v_lshlrev_b32_e32 v34, 16, v103
	v_and_b32_e32 v35, 0xffff0000, v103
	v_lshlrev_b32_e32 v52, 16, v104
	v_and_b32_e32 v53, 0xffff0000, v104
	v_lshlrev_b32_e32 v54, 16, v105
	v_and_b32_e32 v55, 0xffff0000, v105
	v_lshlrev_b32_e32 v56, 16, v106
	v_and_b32_e32 v57, 0xffff0000, v106
	v_lshlrev_b32_e32 v58, 16, v107
	v_and_b32_e32 v59, 0xffff0000, v107
	v_pk_mul_f32 v[60:61], v[4:5], v[36:37]
	v_pk_mul_f32 v[62:63], v[6:7], v[38:39]
	v_pk_mul_f32 v[64:65], v[8:9], v[40:41]
	v_pk_mul_f32 v[66:67], v[10:11], v[42:43]
	v_pk_fma_f32 v[60:61], v[12:13], v[44:45], v[60:61]
	v_pk_fma_f32 v[62:63], v[14:15], v[46:47], v[62:63]
	v_pk_fma_f32 v[64:65], v[16:17], v[48:49], v[64:65]
	v_pk_fma_f32 v[66:67], v[18:19], v[50:51], v[66:67]
	v_pk_fma_f32 v[60:61], v[20:21], v[28:29], v[60:61]
	v_pk_fma_f32 v[62:63], v[22:23], v[30:31], v[62:63]
	v_pk_fma_f32 v[64:65], v[24:25], v[32:33], v[64:65]
	v_pk_fma_f32 v[66:67], v[26:27], v[34:35], v[66:67]
	v_pk_mul_f32 v[60:61], v[60:61], v[52:53]
	v_pk_mul_f32 v[62:63], v[62:63], v[54:55]
	v_pk_mul_f32 v[64:65], v[64:65], v[56:57]
	v_pk_mul_f32 v[66:67], v[66:67], v[58:59]
	v_cvt_pk_bf16_f32 v100, v60, v61
	v_cvt_pk_bf16_f32 v101, v62, v63
	v_cvt_pk_bf16_f32 v102, v64, v65
	v_cvt_pk_bf16_f32 v103, v66, v67
	global_store_dwordx4 v2, v[100:103], s[20:21]
	s_add_u32 s20, s20, 0x1000
	s_addc_u32 s21, s21, 0
	s_add_i32 s11, s11, 1
	s_cmp_eq_u32 s11, 0x1010
	s_cselect_b32 s11, 0, s11
	global_load_dwordx4 v[100:103], v2, s[18:19]
	global_load_dwordx4 v[104:107], v2, s[16:17]
	s_add_u32 s18, s18, 0x1000
	s_addc_u32 s19, s19, 0
	s_add_u32 s16, s16, 0x1000
	s_addc_u32 s17, s17, 0
	s_waitcnt vmcnt(30)
	s_cmp_eq_u32 s11, 0
	s_cbranch_scc0 .Lconv_nz16
	v_mov_b32_e32 v28, 0
	v_mov_b32_e32 v29, 0
	v_mov_b32_e32 v30, 0
	v_mov_b32_e32 v31, 0
	v_mov_b32_e32 v32, 0
	v_mov_b32_e32 v33, 0
	v_mov_b32_e32 v34, 0
	v_mov_b32_e32 v35, 0
	v_mov_b32_e32 v44, 0
	v_mov_b32_e32 v45, 0
	v_mov_b32_e32 v46, 0
	v_mov_b32_e32 v47, 0
	v_mov_b32_e32 v48, 0
	v_mov_b32_e32 v49, 0
	v_mov_b32_e32 v50, 0
	v_mov_b32_e32 v51, 0
.Lconv_nz16:
	v_lshlrev_b32_e32 v36, 16, v108
	v_and_b32_e32 v37, 0xffff0000, v108
	v_lshlrev_b32_e32 v38, 16, v109
	v_and_b32_e32 v39, 0xffff0000, v109
	v_lshlrev_b32_e32 v40, 16, v110
	v_and_b32_e32 v41, 0xffff0000, v110
	v_lshlrev_b32_e32 v42, 16, v111
	v_and_b32_e32 v43, 0xffff0000, v111
	v_lshlrev_b32_e32 v52, 16, v112
	v_and_b32_e32 v53, 0xffff0000, v112
	v_lshlrev_b32_e32 v54, 16, v113
	v_and_b32_e32 v55, 0xffff0000, v113
	v_lshlrev_b32_e32 v56, 16, v114
	v_and_b32_e32 v57, 0xffff0000, v114
	v_lshlrev_b32_e32 v58, 16, v115
	v_and_b32_e32 v59, 0xffff0000, v115
	v_pk_mul_f32 v[60:61], v[4:5], v[44:45]
	v_pk_mul_f32 v[62:63], v[6:7], v[46:47]
	v_pk_mul_f32 v[64:65], v[8:9], v[48:49]
	v_pk_mul_f32 v[66:67], v[10:11], v[50:51]
	v_pk_fma_f32 v[60:61], v[12:13], v[28:29], v[60:61]
	v_pk_fma_f32 v[62:63], v[14:15], v[30:31], v[62:63]
	v_pk_fma_f32 v[64:65], v[16:17], v[32:33], v[64:65]
	v_pk_fma_f32 v[66:67], v[18:19], v[34:35], v[66:67]
	v_pk_fma_f32 v[60:61], v[20:21], v[36:37], v[60:61]
	v_pk_fma_f32 v[62:63], v[22:23], v[38:39], v[62:63]
	v_pk_fma_f32 v[64:65], v[24:25], v[40:41], v[64:65]
	v_pk_fma_f32 v[66:67], v[26:27], v[42:43], v[66:67]
	v_pk_mul_f32 v[60:61], v[60:61], v[52:53]
	v_pk_mul_f32 v[62:63], v[62:63], v[54:55]
	v_pk_mul_f32 v[64:65], v[64:65], v[56:57]
	v_pk_mul_f32 v[66:67], v[66:67], v[58:59]
	v_cvt_pk_bf16_f32 v108, v60, v61
	v_cvt_pk_bf16_f32 v109, v62, v63
	v_cvt_pk_bf16_f32 v110, v64, v65
	v_cvt_pk_bf16_f32 v111, v66, v67
	global_store_dwordx4 v2, v[108:111], s[20:21]
	s_add_u32 s20, s20, 0x1000
	s_addc_u32 s21, s21, 0
	s_add_i32 s11, s11, 1
	s_cmp_eq_u32 s11, 0x1010
	s_cselect_b32 s11, 0, s11
	global_load_dwordx4 v[108:111], v2, s[18:19]
	global_load_dwordx4 v[112:115], v2, s[16:17]
	s_add_u32 s18, s18, 0x1000
	s_addc_u32 s19, s19, 0
	s_add_u32 s16, s16, 0x1000
	s_addc_u32 s17, s17, 0
	s_waitcnt vmcnt(30)
	s_cmp_eq_u32 s11, 0
	s_cbranch_scc0 .Lconv_nz17
	v_mov_b32_e32 v36, 0
	v_mov_b32_e32 v37, 0
	v_mov_b32_e32 v38, 0
	v_mov_b32_e32 v39, 0
	v_mov_b32_e32 v40, 0
	v_mov_b32_e32 v41, 0
	v_mov_b32_e32 v42, 0
	v_mov_b32_e32 v43, 0
	v_mov_b32_e32 v28, 0
	v_mov_b32_e32 v29, 0
	v_mov_b32_e32 v30, 0
	v_mov_b32_e32 v31, 0
	v_mov_b32_e32 v32, 0
	v_mov_b32_e32 v33, 0
	v_mov_b32_e32 v34, 0
	v_mov_b32_e32 v35, 0
.Lconv_nz17:
	v_lshlrev_b32_e32 v44, 16, v116
	v_and_b32_e32 v45, 0xffff0000, v116
	v_lshlrev_b32_e32 v46, 16, v117
	v_and_b32_e32 v47, 0xffff0000, v117
	v_lshlrev_b32_e32 v48, 16, v118
	v_and_b32_e32 v49, 0xffff0000, v118
	v_lshlrev_b32_e32 v50, 16, v119
	v_and_b32_e32 v51, 0xffff0000, v119
	v_lshlrev_b32_e32 v52, 16, v120
	v_and_b32_e32 v53, 0xffff0000, v120
	v_lshlrev_b32_e32 v54, 16, v121
	v_and_b32_e32 v55, 0xffff0000, v121
	v_lshlrev_b32_e32 v56, 16, v122
	v_and_b32_e32 v57, 0xffff0000, v122
	v_lshlrev_b32_e32 v58, 16, v123
	v_and_b32_e32 v59, 0xffff0000, v123
	v_pk_mul_f32 v[60:61], v[4:5], v[28:29]
	v_pk_mul_f32 v[62:63], v[6:7], v[30:31]
	v_pk_mul_f32 v[64:65], v[8:9], v[32:33]
	v_pk_mul_f32 v[66:67], v[10:11], v[34:35]
	v_pk_fma_f32 v[60:61], v[12:13], v[36:37], v[60:61]
	v_pk_fma_f32 v[62:63], v[14:15], v[38:39], v[62:63]
	v_pk_fma_f32 v[64:65], v[16:17], v[40:41], v[64:65]
	v_pk_fma_f32 v[66:67], v[18:19], v[42:43], v[66:67]
	v_pk_fma_f32 v[60:61], v[20:21], v[44:45], v[60:61]
	v_pk_fma_f32 v[62:63], v[22:23], v[46:47], v[62:63]
	v_pk_fma_f32 v[64:65], v[24:25], v[48:49], v[64:65]
	v_pk_fma_f32 v[66:67], v[26:27], v[50:51], v[66:67]
	v_pk_mul_f32 v[60:61], v[60:61], v[52:53]
	v_pk_mul_f32 v[62:63], v[62:63], v[54:55]
	v_pk_mul_f32 v[64:65], v[64:65], v[56:57]
	v_pk_mul_f32 v[66:67], v[66:67], v[58:59]
	v_cvt_pk_bf16_f32 v116, v60, v61
	v_cvt_pk_bf16_f32 v117, v62, v63
	v_cvt_pk_bf16_f32 v118, v64, v65
	v_cvt_pk_bf16_f32 v119, v66, v67
	global_store_dwordx4 v2, v[116:119], s[20:21]
	s_add_u32 s20, s20, 0x1000
	s_addc_u32 s21, s21, 0
	s_add_i32 s11, s11, 1
	s_cmp_eq_u32 s11, 0x1010
	s_cselect_b32 s11, 0, s11
	global_load_dwordx4 v[116:119], v2, s[18:19]
	global_load_dwordx4 v[120:123], v2, s[16:17]
	s_add_u32 s18, s18, 0x1000
	s_addc_u32 s19, s19, 0
	s_add_u32 s16, s16, 0x1000
	s_addc_u32 s17, s17, 0
	s_waitcnt vmcnt(30)
	s_cmp_eq_u32 s11, 0
	s_cbranch_scc0 .Lconv_nz18
	v_mov_b32_e32 v44, 0
	v_mov_b32_e32 v45, 0
	v_mov_b32_e32 v46, 0
	v_mov_b32_e32 v47, 0
	v_mov_b32_e32 v48, 0
	v_mov_b32_e32 v49, 0
	v_mov_b32_e32 v50, 0
	v_mov_b32_e32 v51, 0
	v_mov_b32_e32 v36, 0
	v_mov_b32_e32 v37, 0
	v_mov_b32_e32 v38, 0
	v_mov_b32_e32 v39, 0
	v_mov_b32_e32 v40, 0
	v_mov_b32_e32 v41, 0
	v_mov_b32_e32 v42, 0
	v_mov_b32_e32 v43, 0
.Lconv_nz18:
	v_lshlrev_b32_e32 v28, 16, v132
	v_and_b32_e32 v29, 0xffff0000, v132
	v_lshlrev_b32_e32 v30, 16, v133
	v_and_b32_e32 v31, 0xffff0000, v133
	v_lshlrev_b32_e32 v32, 16, v134
	v_and_b32_e32 v33, 0xffff0000, v134
	v_lshlrev_b32_e32 v34, 16, v135
	v_and_b32_e32 v35, 0xffff0000, v135
	v_lshlrev_b32_e32 v52, 16, v136
	v_and_b32_e32 v53, 0xffff0000, v136
	v_lshlrev_b32_e32 v54, 16, v137
	v_and_b32_e32 v55, 0xffff0000, v137
	v_lshlrev_b32_e32 v56, 16, v138
	v_and_b32_e32 v57, 0xffff0000, v138
	v_lshlrev_b32_e32 v58, 16, v139
	v_and_b32_e32 v59, 0xffff0000, v139
	v_pk_mul_f32 v[60:61], v[4:5], v[36:37]
	v_pk_mul_f32 v[62:63], v[6:7], v[38:39]
	v_pk_mul_f32 v[64:65], v[8:9], v[40:41]
	v_pk_mul_f32 v[66:67], v[10:11], v[42:43]
	v_pk_fma_f32 v[60:61], v[12:13], v[44:45], v[60:61]
	v_pk_fma_f32 v[62:63], v[14:15], v[46:47], v[62:63]
	v_pk_fma_f32 v[64:65], v[16:17], v[48:49], v[64:65]
	v_pk_fma_f32 v[66:67], v[18:19], v[50:51], v[66:67]
	v_pk_fma_f32 v[60:61], v[20:21], v[28:29], v[60:61]
	v_pk_fma_f32 v[62:63], v[22:23], v[30:31], v[62:63]
	v_pk_fma_f32 v[64:65], v[24:25], v[32:33], v[64:65]
	v_pk_fma_f32 v[66:67], v[26:27], v[34:35], v[66:67]
	v_pk_mul_f32 v[60:61], v[60:61], v[52:53]
	v_pk_mul_f32 v[62:63], v[62:63], v[54:55]
	v_pk_mul_f32 v[64:65], v[64:65], v[56:57]
	v_pk_mul_f32 v[66:67], v[66:67], v[58:59]
	v_cvt_pk_bf16_f32 v132, v60, v61
	v_cvt_pk_bf16_f32 v133, v62, v63
	v_cvt_pk_bf16_f32 v134, v64, v65
	v_cvt_pk_bf16_f32 v135, v66, v67
	global_store_dwordx4 v2, v[132:135], s[20:21]
	s_add_u32 s20, s20, 0x1000
	s_addc_u32 s21, s21, 0
	s_add_i32 s11, s11, 1
	s_cmp_eq_u32 s11, 0x1010
	s_cselect_b32 s11, 0, s11
	global_load_dwordx4 v[132:135], v2, s[18:19]
	global_load_dwordx4 v[136:139], v2, s[16:17]
	s_add_u32 s18, s18, 0x1000
	s_addc_u32 s19, s19, 0
	s_add_u32 s16, s16, 0x1000
	s_addc_u32 s17, s17, 0
	s_waitcnt vmcnt(30)
	s_cmp_eq_u32 s11, 0
	s_cbranch_scc0 .Lconv_nz19
	v_mov_b32_e32 v28, 0
	v_mov_b32_e32 v29, 0
	v_mov_b32_e32 v30, 0
	v_mov_b32_e32 v31, 0
	v_mov_b32_e32 v32, 0
	v_mov_b32_e32 v33, 0
	v_mov_b32_e32 v34, 0
	v_mov_b32_e32 v35, 0
	v_mov_b32_e32 v44, 0
	v_mov_b32_e32 v45, 0
	v_mov_b32_e32 v46, 0
	v_mov_b32_e32 v47, 0
	v_mov_b32_e32 v48, 0
	v_mov_b32_e32 v49, 0
	v_mov_b32_e32 v50, 0
	v_mov_b32_e32 v51, 0
.Lconv_nz19:
	v_lshlrev_b32_e32 v36, 16, v140
	v_and_b32_e32 v37, 0xffff0000, v140
	v_lshlrev_b32_e32 v38, 16, v141
	v_and_b32_e32 v39, 0xffff0000, v141
	v_lshlrev_b32_e32 v40, 16, v142
	v_and_b32_e32 v41, 0xffff0000, v142
	v_lshlrev_b32_e32 v42, 16, v143
	v_and_b32_e32 v43, 0xffff0000, v143
	v_lshlrev_b32_e32 v52, 16, v144
	v_and_b32_e32 v53, 0xffff0000, v144
	v_lshlrev_b32_e32 v54, 16, v145
	v_and_b32_e32 v55, 0xffff0000, v145
	v_lshlrev_b32_e32 v56, 16, v146
	v_and_b32_e32 v57, 0xffff0000, v146
	v_lshlrev_b32_e32 v58, 16, v147
	v_and_b32_e32 v59, 0xffff0000, v147
	v_pk_mul_f32 v[60:61], v[4:5], v[44:45]
	v_pk_mul_f32 v[62:63], v[6:7], v[46:47]
	v_pk_mul_f32 v[64:65], v[8:9], v[48:49]
	v_pk_mul_f32 v[66:67], v[10:11], v[50:51]
	v_pk_fma_f32 v[60:61], v[12:13], v[28:29], v[60:61]
	v_pk_fma_f32 v[62:63], v[14:15], v[30:31], v[62:63]
	v_pk_fma_f32 v[64:65], v[16:17], v[32:33], v[64:65]
	v_pk_fma_f32 v[66:67], v[18:19], v[34:35], v[66:67]
	v_pk_fma_f32 v[60:61], v[20:21], v[36:37], v[60:61]
	v_pk_fma_f32 v[62:63], v[22:23], v[38:39], v[62:63]
	v_pk_fma_f32 v[64:65], v[24:25], v[40:41], v[64:65]
	v_pk_fma_f32 v[66:67], v[26:27], v[42:43], v[66:67]
	v_pk_mul_f32 v[60:61], v[60:61], v[52:53]
	v_pk_mul_f32 v[62:63], v[62:63], v[54:55]
	v_pk_mul_f32 v[64:65], v[64:65], v[56:57]
	v_pk_mul_f32 v[66:67], v[66:67], v[58:59]
	v_cvt_pk_bf16_f32 v140, v60, v61
	v_cvt_pk_bf16_f32 v141, v62, v63
	v_cvt_pk_bf16_f32 v142, v64, v65
	v_cvt_pk_bf16_f32 v143, v66, v67
	global_store_dwordx4 v2, v[140:143], s[20:21]
	s_add_u32 s20, s20, 0x1000
	s_addc_u32 s21, s21, 0
	s_add_i32 s11, s11, 1
	s_cmp_eq_u32 s11, 0x1010
	s_cselect_b32 s11, 0, s11
	global_load_dwordx4 v[140:143], v2, s[18:19]
	global_load_dwordx4 v[144:147], v2, s[16:17]
	s_add_u32 s18, s18, 0x1000
	s_addc_u32 s19, s19, 0
	s_add_u32 s16, s16, 0x1000
	s_addc_u32 s17, s17, 0
	s_waitcnt vmcnt(30)
	s_cmp_eq_u32 s11, 0
	s_cbranch_scc0 .Lconv_nz20
	v_mov_b32_e32 v36, 0
	v_mov_b32_e32 v37, 0
	v_mov_b32_e32 v38, 0
	v_mov_b32_e32 v39, 0
	v_mov_b32_e32 v40, 0
	v_mov_b32_e32 v41, 0
	v_mov_b32_e32 v42, 0
	v_mov_b32_e32 v43, 0
	v_mov_b32_e32 v28, 0
	v_mov_b32_e32 v29, 0
	v_mov_b32_e32 v30, 0
	v_mov_b32_e32 v31, 0
	v_mov_b32_e32 v32, 0
	v_mov_b32_e32 v33, 0
	v_mov_b32_e32 v34, 0
	v_mov_b32_e32 v35, 0
.Lconv_nz20:
	v_lshlrev_b32_e32 v44, 16, v148
	v_and_b32_e32 v45, 0xffff0000, v148
	v_lshlrev_b32_e32 v46, 16, v149
	v_and_b32_e32 v47, 0xffff0000, v149
	v_lshlrev_b32_e32 v48, 16, v150
	v_and_b32_e32 v49, 0xffff0000, v150
	v_lshlrev_b32_e32 v50, 16, v151
	v_and_b32_e32 v51, 0xffff0000, v151
	v_lshlrev_b32_e32 v52, 16, v152
	v_and_b32_e32 v53, 0xffff0000, v152
	v_lshlrev_b32_e32 v54, 16, v153
	v_and_b32_e32 v55, 0xffff0000, v153
	v_lshlrev_b32_e32 v56, 16, v154
	v_and_b32_e32 v57, 0xffff0000, v154
	v_lshlrev_b32_e32 v58, 16, v155
	v_and_b32_e32 v59, 0xffff0000, v155
	v_pk_mul_f32 v[60:61], v[4:5], v[28:29]
	v_pk_mul_f32 v[62:63], v[6:7], v[30:31]
	v_pk_mul_f32 v[64:65], v[8:9], v[32:33]
	v_pk_mul_f32 v[66:67], v[10:11], v[34:35]
	v_pk_fma_f32 v[60:61], v[12:13], v[36:37], v[60:61]
	v_pk_fma_f32 v[62:63], v[14:15], v[38:39], v[62:63]
	v_pk_fma_f32 v[64:65], v[16:17], v[40:41], v[64:65]
	v_pk_fma_f32 v[66:67], v[18:19], v[42:43], v[66:67]
	v_pk_fma_f32 v[60:61], v[20:21], v[44:45], v[60:61]
	v_pk_fma_f32 v[62:63], v[22:23], v[46:47], v[62:63]
	v_pk_fma_f32 v[64:65], v[24:25], v[48:49], v[64:65]
	v_pk_fma_f32 v[66:67], v[26:27], v[50:51], v[66:67]
	v_pk_mul_f32 v[60:61], v[60:61], v[52:53]
	v_pk_mul_f32 v[62:63], v[62:63], v[54:55]
	v_pk_mul_f32 v[64:65], v[64:65], v[56:57]
	v_pk_mul_f32 v[66:67], v[66:67], v[58:59]
	v_cvt_pk_bf16_f32 v148, v60, v61
	v_cvt_pk_bf16_f32 v149, v62, v63
	v_cvt_pk_bf16_f32 v150, v64, v65
	v_cvt_pk_bf16_f32 v151, v66, v67
	global_store_dwordx4 v2, v[148:151], s[20:21]
	s_add_u32 s20, s20, 0x1000
	s_addc_u32 s21, s21, 0
	s_add_i32 s11, s11, 1
	s_cmp_eq_u32 s11, 0x1010
	s_cselect_b32 s11, 0, s11
	global_load_dwordx4 v[148:151], v2, s[18:19]
	global_load_dwordx4 v[152:155], v2, s[16:17]
	s_add_u32 s18, s18, 0x1000
	s_addc_u32 s19, s19, 0
	s_add_u32 s16, s16, 0x1000
	s_addc_u32 s17, s17, 0
	s_waitcnt vmcnt(30)
	s_cmp_eq_u32 s11, 0
	s_cbranch_scc0 .Lconv_nz21
	v_mov_b32_e32 v44, 0
	v_mov_b32_e32 v45, 0
	v_mov_b32_e32 v46, 0
	v_mov_b32_e32 v47, 0
	v_mov_b32_e32 v48, 0
	v_mov_b32_e32 v49, 0
	v_mov_b32_e32 v50, 0
	v_mov_b32_e32 v51, 0
	v_mov_b32_e32 v36, 0
	v_mov_b32_e32 v37, 0
	v_mov_b32_e32 v38, 0
	v_mov_b32_e32 v39, 0
	v_mov_b32_e32 v40, 0
	v_mov_b32_e32 v41, 0
	v_mov_b32_e32 v42, 0
	v_mov_b32_e32 v43, 0
.Lconv_nz21:
	v_lshlrev_b32_e32 v28, 16, v156
	v_and_b32_e32 v29, 0xffff0000, v156
	v_lshlrev_b32_e32 v30, 16, v157
	v_and_b32_e32 v31, 0xffff0000, v157
	v_lshlrev_b32_e32 v32, 16, v158
	v_and_b32_e32 v33, 0xffff0000, v158
	v_lshlrev_b32_e32 v34, 16, v159
	v_and_b32_e32 v35, 0xffff0000, v159
	v_lshlrev_b32_e32 v52, 16, v160
	v_and_b32_e32 v53, 0xffff0000, v160
	v_lshlrev_b32_e32 v54, 16, v161
	v_and_b32_e32 v55, 0xffff0000, v161
	v_lshlrev_b32_e32 v56, 16, v162
	v_and_b32_e32 v57, 0xffff0000, v162
	v_lshlrev_b32_e32 v58, 16, v163
	v_and_b32_e32 v59, 0xffff0000, v163
	v_pk_mul_f32 v[60:61], v[4:5], v[36:37]
	v_pk_mul_f32 v[62:63], v[6:7], v[38:39]
	v_pk_mul_f32 v[64:65], v[8:9], v[40:41]
	v_pk_mul_f32 v[66:67], v[10:11], v[42:43]
	v_pk_fma_f32 v[60:61], v[12:13], v[44:45], v[60:61]
	v_pk_fma_f32 v[62:63], v[14:15], v[46:47], v[62:63]
	v_pk_fma_f32 v[64:65], v[16:17], v[48:49], v[64:65]
	v_pk_fma_f32 v[66:67], v[18:19], v[50:51], v[66:67]
	v_pk_fma_f32 v[60:61], v[20:21], v[28:29], v[60:61]
	v_pk_fma_f32 v[62:63], v[22:23], v[30:31], v[62:63]
	v_pk_fma_f32 v[64:65], v[24:25], v[32:33], v[64:65]
	v_pk_fma_f32 v[66:67], v[26:27], v[34:35], v[66:67]
	v_pk_mul_f32 v[60:61], v[60:61], v[52:53]
	v_pk_mul_f32 v[62:63], v[62:63], v[54:55]
	v_pk_mul_f32 v[64:65], v[64:65], v[56:57]
	v_pk_mul_f32 v[66:67], v[66:67], v[58:59]
	v_cvt_pk_bf16_f32 v156, v60, v61
	v_cvt_pk_bf16_f32 v157, v62, v63
	v_cvt_pk_bf16_f32 v158, v64, v65
	v_cvt_pk_bf16_f32 v159, v66, v67
	global_store_dwordx4 v2, v[156:159], s[20:21]
	s_add_u32 s20, s20, 0x1000
	s_addc_u32 s21, s21, 0
	s_add_i32 s11, s11, 1
	s_cmp_eq_u32 s11, 0x1010
	s_cselect_b32 s11, 0, s11
	global_load_dwordx4 v[156:159], v2, s[18:19]
	global_load_dwordx4 v[160:163], v2, s[16:17]
	s_add_u32 s18, s18, 0x1000
	s_addc_u32 s19, s19, 0
	s_add_u32 s16, s16, 0x1000
	s_addc_u32 s17, s17, 0
	s_waitcnt vmcnt(30)
	s_cmp_eq_u32 s11, 0
	s_cbranch_scc0 .Lconv_nz22
	v_mov_b32_e32 v28, 0
	v_mov_b32_e32 v29, 0
	v_mov_b32_e32 v30, 0
	v_mov_b32_e32 v31, 0
	v_mov_b32_e32 v32, 0
	v_mov_b32_e32 v33, 0
	v_mov_b32_e32 v34, 0
	v_mov_b32_e32 v35, 0
	v_mov_b32_e32 v44, 0
	v_mov_b32_e32 v45, 0
	v_mov_b32_e32 v46, 0
	v_mov_b32_e32 v47, 0
	v_mov_b32_e32 v48, 0
	v_mov_b32_e32 v49, 0
	v_mov_b32_e32 v50, 0
	v_mov_b32_e32 v51, 0
.Lconv_nz22:
	v_lshlrev_b32_e32 v36, 16, v68
	v_and_b32_e32 v37, 0xffff0000, v68
	v_lshlrev_b32_e32 v38, 16, v69
	v_and_b32_e32 v39, 0xffff0000, v69
	v_lshlrev_b32_e32 v40, 16, v70
	v_and_b32_e32 v41, 0xffff0000, v70
	v_lshlrev_b32_e32 v42, 16, v71
	v_and_b32_e32 v43, 0xffff0000, v71
	v_lshlrev_b32_e32 v52, 16, v72
	v_and_b32_e32 v53, 0xffff0000, v72
	v_lshlrev_b32_e32 v54, 16, v73
	v_and_b32_e32 v55, 0xffff0000, v73
	v_lshlrev_b32_e32 v56, 16, v74
	v_and_b32_e32 v57, 0xffff0000, v74
	v_lshlrev_b32_e32 v58, 16, v75
	v_and_b32_e32 v59, 0xffff0000, v75
	v_pk_mul_f32 v[60:61], v[4:5], v[44:45]
	v_pk_mul_f32 v[62:63], v[6:7], v[46:47]
	v_pk_mul_f32 v[64:65], v[8:9], v[48:49]
	v_pk_mul_f32 v[66:67], v[10:11], v[50:51]
	v_pk_fma_f32 v[60:61], v[12:13], v[28:29], v[60:61]
	v_pk_fma_f32 v[62:63], v[14:15], v[30:31], v[62:63]
	v_pk_fma_f32 v[64:65], v[16:17], v[32:33], v[64:65]
	v_pk_fma_f32 v[66:67], v[18:19], v[34:35], v[66:67]
	v_pk_fma_f32 v[60:61], v[20:21], v[36:37], v[60:61]
	v_pk_fma_f32 v[62:63], v[22:23], v[38:39], v[62:63]
	v_pk_fma_f32 v[64:65], v[24:25], v[40:41], v[64:65]
	v_pk_fma_f32 v[66:67], v[26:27], v[42:43], v[66:67]
	v_pk_mul_f32 v[60:61], v[60:61], v[52:53]
	v_pk_mul_f32 v[62:63], v[62:63], v[54:55]
	v_pk_mul_f32 v[64:65], v[64:65], v[56:57]
	v_pk_mul_f32 v[66:67], v[66:67], v[58:59]
	v_cvt_pk_bf16_f32 v68, v60, v61
	v_cvt_pk_bf16_f32 v69, v62, v63
	v_cvt_pk_bf16_f32 v70, v64, v65
	v_cvt_pk_bf16_f32 v71, v66, v67
	global_store_dwordx4 v2, v[68:71], s[20:21]
	s_add_u32 s20, s20, 0x1000
	s_addc_u32 s21, s21, 0
	s_add_i32 s11, s11, 1
	s_cmp_eq_u32 s11, 0x1010
	s_cselect_b32 s11, 0, s11
	s_waitcnt vmcnt(28)
	s_cmp_eq_u32 s11, 0
	s_cbranch_scc0 .Lconv_nz23
	v_mov_b32_e32 v36, 0
	v_mov_b32_e32 v37, 0
	v_mov_b32_e32 v38, 0
	v_mov_b32_e32 v39, 0
	v_mov_b32_e32 v40, 0
	v_mov_b32_e32 v41, 0
	v_mov_b32_e32 v42, 0
	v_mov_b32_e32 v43, 0
	v_mov_b32_e32 v28, 0
	v_mov_b32_e32 v29, 0
	v_mov_b32_e32 v30, 0
	v_mov_b32_e32 v31, 0
	v_mov_b32_e32 v32, 0
	v_mov_b32_e32 v33, 0
	v_mov_b32_e32 v34, 0
	v_mov_b32_e32 v35, 0
.Lconv_nz23:
	v_lshlrev_b32_e32 v44, 16, v76
	v_and_b32_e32 v45, 0xffff0000, v76
	v_lshlrev_b32_e32 v46, 16, v77
	v_and_b32_e32 v47, 0xffff0000, v77
	v_lshlrev_b32_e32 v48, 16, v78
	v_and_b32_e32 v49, 0xffff0000, v78
	v_lshlrev_b32_e32 v50, 16, v79
	v_and_b32_e32 v51, 0xffff0000, v79
	v_lshlrev_b32_e32 v52, 16, v80
	v_and_b32_e32 v53, 0xffff0000, v80
	v_lshlrev_b32_e32 v54, 16, v81
	v_and_b32_e32 v55, 0xffff0000, v81
	v_lshlrev_b32_e32 v56, 16, v82
	v_and_b32_e32 v57, 0xffff0000, v82
	v_lshlrev_b32_e32 v58, 16, v83
	v_and_b32_e32 v59, 0xffff0000, v83
	v_pk_mul_f32 v[60:61], v[4:5], v[28:29]
	v_pk_mul_f32 v[62:63], v[6:7], v[30:31]
	v_pk_mul_f32 v[64:65], v[8:9], v[32:33]
	v_pk_mul_f32 v[66:67], v[10:11], v[34:35]
	v_pk_fma_f32 v[60:61], v[12:13], v[36:37], v[60:61]
	v_pk_fma_f32 v[62:63], v[14:15], v[38:39], v[62:63]
	v_pk_fma_f32 v[64:65], v[16:17], v[40:41], v[64:65]
	v_pk_fma_f32 v[66:67], v[18:19], v[42:43], v[66:67]
	v_pk_fma_f32 v[60:61], v[20:21], v[44:45], v[60:61]
	v_pk_fma_f32 v[62:63], v[22:23], v[46:47], v[62:63]
	v_pk_fma_f32 v[64:65], v[24:25], v[48:49], v[64:65]
	v_pk_fma_f32 v[66:67], v[26:27], v[50:51], v[66:67]
	v_pk_mul_f32 v[60:61], v[60:61], v[52:53]
	v_pk_mul_f32 v[62:63], v[62:63], v[54:55]
	v_pk_mul_f32 v[64:65], v[64:65], v[56:57]
	v_pk_mul_f32 v[66:67], v[66:67], v[58:59]
	v_cvt_pk_bf16_f32 v76, v60, v61
	v_cvt_pk_bf16_f32 v77, v62, v63
	v_cvt_pk_bf16_f32 v78, v64, v65
	v_cvt_pk_bf16_f32 v79, v66, v67
	global_store_dwordx4 v2, v[76:79], s[20:21]
	s_add_u32 s20, s20, 0x1000
	s_addc_u32 s21, s21, 0
	s_add_i32 s11, s11, 1
	s_cmp_eq_u32 s11, 0x1010
	s_cselect_b32 s11, 0, s11
	s_waitcnt vmcnt(26)
	s_cmp_eq_u32 s11, 0
	s_cbranch_scc0 .Lconv_nz24
	v_mov_b32_e32 v44, 0
	v_mov_b32_e32 v45, 0
	v_mov_b32_e32 v46, 0
	v_mov_b32_e32 v47, 0
	v_mov_b32_e32 v48, 0
	v_mov_b32_e32 v49, 0
	v_mov_b32_e32 v50, 0
	v_mov_b32_e32 v51, 0
	v_mov_b32_e32 v36, 0
	v_mov_b32_e32 v37, 0
	v_mov_b32_e32 v38, 0
	v_mov_b32_e32 v39, 0
	v_mov_b32_e32 v40, 0
	v_mov_b32_e32 v41, 0
	v_mov_b32_e32 v42, 0
	v_mov_b32_e32 v43, 0
.Lconv_nz24:
	v_lshlrev_b32_e32 v28, 16, v84
	v_and_b32_e32 v29, 0xffff0000, v84
	v_lshlrev_b32_e32 v30, 16, v85
	v_and_b32_e32 v31, 0xffff0000, v85
	v_lshlrev_b32_e32 v32, 16, v86
	v_and_b32_e32 v33, 0xffff0000, v86
	v_lshlrev_b32_e32 v34, 16, v87
	v_and_b32_e32 v35, 0xffff0000, v87
	v_lshlrev_b32_e32 v52, 16, v88
	v_and_b32_e32 v53, 0xffff0000, v88
	v_lshlrev_b32_e32 v54, 16, v89
	v_and_b32_e32 v55, 0xffff0000, v89
	v_lshlrev_b32_e32 v56, 16, v90
	v_and_b32_e32 v57, 0xffff0000, v90
	v_lshlrev_b32_e32 v58, 16, v91
	v_and_b32_e32 v59, 0xffff0000, v91
	v_pk_mul_f32 v[60:61], v[4:5], v[36:37]
	v_pk_mul_f32 v[62:63], v[6:7], v[38:39]
	v_pk_mul_f32 v[64:65], v[8:9], v[40:41]
	v_pk_mul_f32 v[66:67], v[10:11], v[42:43]
	v_pk_fma_f32 v[60:61], v[12:13], v[44:45], v[60:61]
	v_pk_fma_f32 v[62:63], v[14:15], v[46:47], v[62:63]
	v_pk_fma_f32 v[64:65], v[16:17], v[48:49], v[64:65]
	v_pk_fma_f32 v[66:67], v[18:19], v[50:51], v[66:67]
	v_pk_fma_f32 v[60:61], v[20:21], v[28:29], v[60:61]
	v_pk_fma_f32 v[62:63], v[22:23], v[30:31], v[62:63]
	v_pk_fma_f32 v[64:65], v[24:25], v[32:33], v[64:65]
	v_pk_fma_f32 v[66:67], v[26:27], v[34:35], v[66:67]
	v_pk_mul_f32 v[60:61], v[60:61], v[52:53]
	v_pk_mul_f32 v[62:63], v[62:63], v[54:55]
	v_pk_mul_f32 v[64:65], v[64:65], v[56:57]
	v_pk_mul_f32 v[66:67], v[66:67], v[58:59]
	v_cvt_pk_bf16_f32 v84, v60, v61
	v_cvt_pk_bf16_f32 v85, v62, v63
	v_cvt_pk_bf16_f32 v86, v64, v65
	v_cvt_pk_bf16_f32 v87, v66, v67
	global_store_dwordx4 v2, v[84:87], s[20:21]
	s_add_u32 s20, s20, 0x1000
	s_addc_u32 s21, s21, 0
	s_add_i32 s11, s11, 1
	s_cmp_eq_u32 s11, 0x1010
	s_cselect_b32 s11, 0, s11
	s_waitcnt vmcnt(24)
	s_cmp_eq_u32 s11, 0
	s_cbranch_scc0 .Lconv_nz25
	v_mov_b32_e32 v28, 0
	v_mov_b32_e32 v29, 0
	v_mov_b32_e32 v30, 0
	v_mov_b32_e32 v31, 0
	v_mov_b32_e32 v32, 0
	v_mov_b32_e32 v33, 0
	v_mov_b32_e32 v34, 0
	v_mov_b32_e32 v35, 0
	v_mov_b32_e32 v44, 0
	v_mov_b32_e32 v45, 0
	v_mov_b32_e32 v46, 0
	v_mov_b32_e32 v47, 0
	v_mov_b32_e32 v48, 0
	v_mov_b32_e32 v49, 0
	v_mov_b32_e32 v50, 0
	v_mov_b32_e32 v51, 0
.Lconv_nz25:
	v_lshlrev_b32_e32 v36, 16, v92
	v_and_b32_e32 v37, 0xffff0000, v92
	v_lshlrev_b32_e32 v38, 16, v93
	v_and_b32_e32 v39, 0xffff0000, v93
	v_lshlrev_b32_e32 v40, 16, v94
	v_and_b32_e32 v41, 0xffff0000, v94
	v_lshlrev_b32_e32 v42, 16, v95
	v_and_b32_e32 v43, 0xffff0000, v95
	v_lshlrev_b32_e32 v52, 16, v96
	v_and_b32_e32 v53, 0xffff0000, v96
	v_lshlrev_b32_e32 v54, 16, v97
	v_and_b32_e32 v55, 0xffff0000, v97
	v_lshlrev_b32_e32 v56, 16, v98
	v_and_b32_e32 v57, 0xffff0000, v98
	v_lshlrev_b32_e32 v58, 16, v99
	v_and_b32_e32 v59, 0xffff0000, v99
	v_pk_mul_f32 v[60:61], v[4:5], v[44:45]
	v_pk_mul_f32 v[62:63], v[6:7], v[46:47]
	v_pk_mul_f32 v[64:65], v[8:9], v[48:49]
	v_pk_mul_f32 v[66:67], v[10:11], v[50:51]
	v_pk_fma_f32 v[60:61], v[12:13], v[28:29], v[60:61]
	v_pk_fma_f32 v[62:63], v[14:15], v[30:31], v[62:63]
	v_pk_fma_f32 v[64:65], v[16:17], v[32:33], v[64:65]
	v_pk_fma_f32 v[66:67], v[18:19], v[34:35], v[66:67]
	v_pk_fma_f32 v[60:61], v[20:21], v[36:37], v[60:61]
	v_pk_fma_f32 v[62:63], v[22:23], v[38:39], v[62:63]
	v_pk_fma_f32 v[64:65], v[24:25], v[40:41], v[64:65]
	v_pk_fma_f32 v[66:67], v[26:27], v[42:43], v[66:67]
	v_pk_mul_f32 v[60:61], v[60:61], v[52:53]
	v_pk_mul_f32 v[62:63], v[62:63], v[54:55]
	v_pk_mul_f32 v[64:65], v[64:65], v[56:57]
	v_pk_mul_f32 v[66:67], v[66:67], v[58:59]
	v_cvt_pk_bf16_f32 v92, v60, v61
	v_cvt_pk_bf16_f32 v93, v62, v63
	v_cvt_pk_bf16_f32 v94, v64, v65
	v_cvt_pk_bf16_f32 v95, v66, v67
	global_store_dwordx4 v2, v[92:95], s[20:21]
	s_add_u32 s20, s20, 0x1000
	s_addc_u32 s21, s21, 0
	s_add_i32 s11, s11, 1
	s_cmp_eq_u32 s11, 0x1010
	s_cselect_b32 s11, 0, s11
	s_waitcnt vmcnt(22)
	s_cmp_eq_u32 s11, 0
	s_cbranch_scc0 .Lconv_nz26
	v_mov_b32_e32 v36, 0
	v_mov_b32_e32 v37, 0
	v_mov_b32_e32 v38, 0
	v_mov_b32_e32 v39, 0
	v_mov_b32_e32 v40, 0
	v_mov_b32_e32 v41, 0
	v_mov_b32_e32 v42, 0
	v_mov_b32_e32 v43, 0
	v_mov_b32_e32 v28, 0
	v_mov_b32_e32 v29, 0
	v_mov_b32_e32 v30, 0
	v_mov_b32_e32 v31, 0
	v_mov_b32_e32 v32, 0
	v_mov_b32_e32 v33, 0
	v_mov_b32_e32 v34, 0
	v_mov_b32_e32 v35, 0
.Lconv_nz26:
	v_lshlrev_b32_e32 v44, 16, v100
	v_and_b32_e32 v45, 0xffff0000, v100
	v_lshlrev_b32_e32 v46, 16, v101
	v_and_b32_e32 v47, 0xffff0000, v101
	v_lshlrev_b32_e32 v48, 16, v102
	v_and_b32_e32 v49, 0xffff0000, v102
	v_lshlrev_b32_e32 v50, 16, v103
	v_and_b32_e32 v51, 0xffff0000, v103
	v_lshlrev_b32_e32 v52, 16, v104
	v_and_b32_e32 v53, 0xffff0000, v104
	v_lshlrev_b32_e32 v54, 16, v105
	v_and_b32_e32 v55, 0xffff0000, v105
	v_lshlrev_b32_e32 v56, 16, v106
	v_and_b32_e32 v57, 0xffff0000, v106
	v_lshlrev_b32_e32 v58, 16, v107
	v_and_b32_e32 v59, 0xffff0000, v107
	v_pk_mul_f32 v[60:61], v[4:5], v[28:29]
	v_pk_mul_f32 v[62:63], v[6:7], v[30:31]
	v_pk_mul_f32 v[64:65], v[8:9], v[32:33]
	v_pk_mul_f32 v[66:67], v[10:11], v[34:35]
	v_pk_fma_f32 v[60:61], v[12:13], v[36:37], v[60:61]
	v_pk_fma_f32 v[62:63], v[14:15], v[38:39], v[62:63]
	v_pk_fma_f32 v[64:65], v[16:17], v[40:41], v[64:65]
	v_pk_fma_f32 v[66:67], v[18:19], v[42:43], v[66:67]
	v_pk_fma_f32 v[60:61], v[20:21], v[44:45], v[60:61]
	v_pk_fma_f32 v[62:63], v[22:23], v[46:47], v[62:63]
	v_pk_fma_f32 v[64:65], v[24:25], v[48:49], v[64:65]
	v_pk_fma_f32 v[66:67], v[26:27], v[50:51], v[66:67]
	v_pk_mul_f32 v[60:61], v[60:61], v[52:53]
	v_pk_mul_f32 v[62:63], v[62:63], v[54:55]
	v_pk_mul_f32 v[64:65], v[64:65], v[56:57]
	v_pk_mul_f32 v[66:67], v[66:67], v[58:59]
	v_cvt_pk_bf16_f32 v100, v60, v61
	v_cvt_pk_bf16_f32 v101, v62, v63
	v_cvt_pk_bf16_f32 v102, v64, v65
	v_cvt_pk_bf16_f32 v103, v66, v67
	global_store_dwordx4 v2, v[100:103], s[20:21]
	s_add_u32 s20, s20, 0x1000
	s_addc_u32 s21, s21, 0
	s_add_i32 s11, s11, 1
	s_cmp_eq_u32 s11, 0x1010
	s_cselect_b32 s11, 0, s11
	s_waitcnt vmcnt(20)
	s_cmp_eq_u32 s11, 0
	s_cbranch_scc0 .Lconv_nz27
	v_mov_b32_e32 v44, 0
	v_mov_b32_e32 v45, 0
	v_mov_b32_e32 v46, 0
	v_mov_b32_e32 v47, 0
	v_mov_b32_e32 v48, 0
	v_mov_b32_e32 v49, 0
	v_mov_b32_e32 v50, 0
	v_mov_b32_e32 v51, 0
	v_mov_b32_e32 v36, 0
	v_mov_b32_e32 v37, 0
	v_mov_b32_e32 v38, 0
	v_mov_b32_e32 v39, 0
	v_mov_b32_e32 v40, 0
	v_mov_b32_e32 v41, 0
	v_mov_b32_e32 v42, 0
	v_mov_b32_e32 v43, 0
.Lconv_nz27:
	v_lshlrev_b32_e32 v28, 16, v108
	v_and_b32_e32 v29, 0xffff0000, v108
	v_lshlrev_b32_e32 v30, 16, v109
	v_and_b32_e32 v31, 0xffff0000, v109
	v_lshlrev_b32_e32 v32, 16, v110
	v_and_b32_e32 v33, 0xffff0000, v110
	v_lshlrev_b32_e32 v34, 16, v111
	v_and_b32_e32 v35, 0xffff0000, v111
	v_lshlrev_b32_e32 v52, 16, v112
	v_and_b32_e32 v53, 0xffff0000, v112
	v_lshlrev_b32_e32 v54, 16, v113
	v_and_b32_e32 v55, 0xffff0000, v113
	v_lshlrev_b32_e32 v56, 16, v114
	v_and_b32_e32 v57, 0xffff0000, v114
	v_lshlrev_b32_e32 v58, 16, v115
	v_and_b32_e32 v59, 0xffff0000, v115
	v_pk_mul_f32 v[60:61], v[4:5], v[36:37]
	v_pk_mul_f32 v[62:63], v[6:7], v[38:39]
	v_pk_mul_f32 v[64:65], v[8:9], v[40:41]
	v_pk_mul_f32 v[66:67], v[10:11], v[42:43]
	v_pk_fma_f32 v[60:61], v[12:13], v[44:45], v[60:61]
	v_pk_fma_f32 v[62:63], v[14:15], v[46:47], v[62:63]
	v_pk_fma_f32 v[64:65], v[16:17], v[48:49], v[64:65]
	v_pk_fma_f32 v[66:67], v[18:19], v[50:51], v[66:67]
	v_pk_fma_f32 v[60:61], v[20:21], v[28:29], v[60:61]
	v_pk_fma_f32 v[62:63], v[22:23], v[30:31], v[62:63]
	v_pk_fma_f32 v[64:65], v[24:25], v[32:33], v[64:65]
	v_pk_fma_f32 v[66:67], v[26:27], v[34:35], v[66:67]
	v_pk_mul_f32 v[60:61], v[60:61], v[52:53]
	v_pk_mul_f32 v[62:63], v[62:63], v[54:55]
	v_pk_mul_f32 v[64:65], v[64:65], v[56:57]
	v_pk_mul_f32 v[66:67], v[66:67], v[58:59]
	v_cvt_pk_bf16_f32 v108, v60, v61
	v_cvt_pk_bf16_f32 v109, v62, v63
	v_cvt_pk_bf16_f32 v110, v64, v65
	v_cvt_pk_bf16_f32 v111, v66, v67
	global_store_dwordx4 v2, v[108:111], s[20:21]
	s_add_u32 s20, s20, 0x1000
	s_addc_u32 s21, s21, 0
	s_add_i32 s11, s11, 1
	s_cmp_eq_u32 s11, 0x1010
	s_cselect_b32 s11, 0, s11
	s_waitcnt vmcnt(18)
	s_cmp_eq_u32 s11, 0
	s_cbranch_scc0 .Lconv_nz28
	v_mov_b32_e32 v28, 0
	v_mov_b32_e32 v29, 0
	v_mov_b32_e32 v30, 0
	v_mov_b32_e32 v31, 0
	v_mov_b32_e32 v32, 0
	v_mov_b32_e32 v33, 0
	v_mov_b32_e32 v34, 0
	v_mov_b32_e32 v35, 0
	v_mov_b32_e32 v44, 0
	v_mov_b32_e32 v45, 0
	v_mov_b32_e32 v46, 0
	v_mov_b32_e32 v47, 0
	v_mov_b32_e32 v48, 0
	v_mov_b32_e32 v49, 0
	v_mov_b32_e32 v50, 0
	v_mov_b32_e32 v51, 0
.Lconv_nz28:
	v_lshlrev_b32_e32 v36, 16, v116
	v_and_b32_e32 v37, 0xffff0000, v116
	v_lshlrev_b32_e32 v38, 16, v117
	v_and_b32_e32 v39, 0xffff0000, v117
	v_lshlrev_b32_e32 v40, 16, v118
	v_and_b32_e32 v41, 0xffff0000, v118
	v_lshlrev_b32_e32 v42, 16, v119
	v_and_b32_e32 v43, 0xffff0000, v119
	v_lshlrev_b32_e32 v52, 16, v120
	v_and_b32_e32 v53, 0xffff0000, v120
	v_lshlrev_b32_e32 v54, 16, v121
	v_and_b32_e32 v55, 0xffff0000, v121
	v_lshlrev_b32_e32 v56, 16, v122
	v_and_b32_e32 v57, 0xffff0000, v122
	v_lshlrev_b32_e32 v58, 16, v123
	v_and_b32_e32 v59, 0xffff0000, v123
	v_pk_mul_f32 v[60:61], v[4:5], v[44:45]
	v_pk_mul_f32 v[62:63], v[6:7], v[46:47]
	v_pk_mul_f32 v[64:65], v[8:9], v[48:49]
	v_pk_mul_f32 v[66:67], v[10:11], v[50:51]
	v_pk_fma_f32 v[60:61], v[12:13], v[28:29], v[60:61]
	v_pk_fma_f32 v[62:63], v[14:15], v[30:31], v[62:63]
	v_pk_fma_f32 v[64:65], v[16:17], v[32:33], v[64:65]
	v_pk_fma_f32 v[66:67], v[18:19], v[34:35], v[66:67]
	v_pk_fma_f32 v[60:61], v[20:21], v[36:37], v[60:61]
	v_pk_fma_f32 v[62:63], v[22:23], v[38:39], v[62:63]
	v_pk_fma_f32 v[64:65], v[24:25], v[40:41], v[64:65]
	v_pk_fma_f32 v[66:67], v[26:27], v[42:43], v[66:67]
	v_pk_mul_f32 v[60:61], v[60:61], v[52:53]
	v_pk_mul_f32 v[62:63], v[62:63], v[54:55]
	v_pk_mul_f32 v[64:65], v[64:65], v[56:57]
	v_pk_mul_f32 v[66:67], v[66:67], v[58:59]
	v_cvt_pk_bf16_f32 v116, v60, v61
	v_cvt_pk_bf16_f32 v117, v62, v63
	v_cvt_pk_bf16_f32 v118, v64, v65
	v_cvt_pk_bf16_f32 v119, v66, v67
	global_store_dwordx4 v2, v[116:119], s[20:21]
	s_add_u32 s20, s20, 0x1000
	s_addc_u32 s21, s21, 0
	s_add_i32 s11, s11, 1
	s_cmp_eq_u32 s11, 0x1010
	s_cselect_b32 s11, 0, s11
	s_waitcnt vmcnt(16)
	s_cmp_eq_u32 s11, 0
	s_cbranch_scc0 .Lconv_nz29
	v_mov_b32_e32 v36, 0
	v_mov_b32_e32 v37, 0
	v_mov_b32_e32 v38, 0
	v_mov_b32_e32 v39, 0
	v_mov_b32_e32 v40, 0
	v_mov_b32_e32 v41, 0
	v_mov_b32_e32 v42, 0
	v_mov_b32_e32 v43, 0
	v_mov_b32_e32 v28, 0
	v_mov_b32_e32 v29, 0
	v_mov_b32_e32 v30, 0
	v_mov_b32_e32 v31, 0
	v_mov_b32_e32 v32, 0
	v_mov_b32_e32 v33, 0
	v_mov_b32_e32 v34, 0
	v_mov_b32_e32 v35, 0
.Lconv_nz29:
	v_lshlrev_b32_e32 v44, 16, v132
	v_and_b32_e32 v45, 0xffff0000, v132
	v_lshlrev_b32_e32 v46, 16, v133
	v_and_b32_e32 v47, 0xffff0000, v133
	v_lshlrev_b32_e32 v48, 16, v134
	v_and_b32_e32 v49, 0xffff0000, v134
	v_lshlrev_b32_e32 v50, 16, v135
	v_and_b32_e32 v51, 0xffff0000, v135
	v_lshlrev_b32_e32 v52, 16, v136
	v_and_b32_e32 v53, 0xffff0000, v136
	v_lshlrev_b32_e32 v54, 16, v137
	v_and_b32_e32 v55, 0xffff0000, v137
	v_lshlrev_b32_e32 v56, 16, v138
	v_and_b32_e32 v57, 0xffff0000, v138
	v_lshlrev_b32_e32 v58, 16, v139
	v_and_b32_e32 v59, 0xffff0000, v139
	v_pk_mul_f32 v[60:61], v[4:5], v[28:29]
	v_pk_mul_f32 v[62:63], v[6:7], v[30:31]
	v_pk_mul_f32 v[64:65], v[8:9], v[32:33]
	v_pk_mul_f32 v[66:67], v[10:11], v[34:35]
	v_pk_fma_f32 v[60:61], v[12:13], v[36:37], v[60:61]
	v_pk_fma_f32 v[62:63], v[14:15], v[38:39], v[62:63]
	v_pk_fma_f32 v[64:65], v[16:17], v[40:41], v[64:65]
	v_pk_fma_f32 v[66:67], v[18:19], v[42:43], v[66:67]
	v_pk_fma_f32 v[60:61], v[20:21], v[44:45], v[60:61]
	v_pk_fma_f32 v[62:63], v[22:23], v[46:47], v[62:63]
	v_pk_fma_f32 v[64:65], v[24:25], v[48:49], v[64:65]
	v_pk_fma_f32 v[66:67], v[26:27], v[50:51], v[66:67]
	v_pk_mul_f32 v[60:61], v[60:61], v[52:53]
	v_pk_mul_f32 v[62:63], v[62:63], v[54:55]
	v_pk_mul_f32 v[64:65], v[64:65], v[56:57]
	v_pk_mul_f32 v[66:67], v[66:67], v[58:59]
	v_cvt_pk_bf16_f32 v132, v60, v61
	v_cvt_pk_bf16_f32 v133, v62, v63
	v_cvt_pk_bf16_f32 v134, v64, v65
	v_cvt_pk_bf16_f32 v135, v66, v67
	global_store_dwordx4 v2, v[132:135], s[20:21]
	s_add_u32 s20, s20, 0x1000
	s_addc_u32 s21, s21, 0
	s_add_i32 s11, s11, 1
	s_cmp_eq_u32 s11, 0x1010
	s_cselect_b32 s11, 0, s11
	s_waitcnt vmcnt(14)
	s_cmp_eq_u32 s11, 0
	s_cbranch_scc0 .Lconv_nz30
	v_mov_b32_e32 v44, 0
	v_mov_b32_e32 v45, 0
	v_mov_b32_e32 v46, 0
	v_mov_b32_e32 v47, 0
	v_mov_b32_e32 v48, 0
	v_mov_b32_e32 v49, 0
	v_mov_b32_e32 v50, 0
	v_mov_b32_e32 v51, 0
	v_mov_b32_e32 v36, 0
	v_mov_b32_e32 v37, 0
	v_mov_b32_e32 v38, 0
	v_mov_b32_e32 v39, 0
	v_mov_b32_e32 v40, 0
	v_mov_b32_e32 v41, 0
	v_mov_b32_e32 v42, 0
	v_mov_b32_e32 v43, 0
.Lconv_nz30:
	v_lshlrev_b32_e32 v28, 16, v140
	v_and_b32_e32 v29, 0xffff0000, v140
	v_lshlrev_b32_e32 v30, 16, v141
	v_and_b32_e32 v31, 0xffff0000, v141
	v_lshlrev_b32_e32 v32, 16, v142
	v_and_b32_e32 v33, 0xffff0000, v142
	v_lshlrev_b32_e32 v34, 16, v143
	v_and_b32_e32 v35, 0xffff0000, v143
	v_lshlrev_b32_e32 v52, 16, v144
	v_and_b32_e32 v53, 0xffff0000, v144
	v_lshlrev_b32_e32 v54, 16, v145
	v_and_b32_e32 v55, 0xffff0000, v145
	v_lshlrev_b32_e32 v56, 16, v146
	v_and_b32_e32 v57, 0xffff0000, v146
	v_lshlrev_b32_e32 v58, 16, v147
	v_and_b32_e32 v59, 0xffff0000, v147
	v_pk_mul_f32 v[60:61], v[4:5], v[36:37]
	v_pk_mul_f32 v[62:63], v[6:7], v[38:39]
	v_pk_mul_f32 v[64:65], v[8:9], v[40:41]
	v_pk_mul_f32 v[66:67], v[10:11], v[42:43]
	v_pk_fma_f32 v[60:61], v[12:13], v[44:45], v[60:61]
	v_pk_fma_f32 v[62:63], v[14:15], v[46:47], v[62:63]
	v_pk_fma_f32 v[64:65], v[16:17], v[48:49], v[64:65]
	v_pk_fma_f32 v[66:67], v[18:19], v[50:51], v[66:67]
	v_pk_fma_f32 v[60:61], v[20:21], v[28:29], v[60:61]
	v_pk_fma_f32 v[62:63], v[22:23], v[30:31], v[62:63]
	v_pk_fma_f32 v[64:65], v[24:25], v[32:33], v[64:65]
	v_pk_fma_f32 v[66:67], v[26:27], v[34:35], v[66:67]
	v_pk_mul_f32 v[60:61], v[60:61], v[52:53]
	v_pk_mul_f32 v[62:63], v[62:63], v[54:55]
	v_pk_mul_f32 v[64:65], v[64:65], v[56:57]
	v_pk_mul_f32 v[66:67], v[66:67], v[58:59]
	v_cvt_pk_bf16_f32 v140, v60, v61
	v_cvt_pk_bf16_f32 v141, v62, v63
	v_cvt_pk_bf16_f32 v142, v64, v65
	v_cvt_pk_bf16_f32 v143, v66, v67
	global_store_dwordx4 v2, v[140:143], s[20:21]
	s_add_u32 s20, s20, 0x1000
	s_addc_u32 s21, s21, 0
	s_add_i32 s11, s11, 1
	s_cmp_eq_u32 s11, 0x1010
	s_cselect_b32 s11, 0, s11
	s_waitcnt vmcnt(12)
	s_cmp_eq_u32 s11, 0
	s_cbranch_scc0 .Lconv_nz31
	v_mov_b32_e32 v28, 0
	v_mov_b32_e32 v29, 0
	v_mov_b32_e32 v30, 0
	v_mov_b32_e32 v31, 0
	v_mov_b32_e32 v32, 0
	v_mov_b32_e32 v33, 0
	v_mov_b32_e32 v34, 0
	v_mov_b32_e32 v35, 0
	v_mov_b32_e32 v44, 0
	v_mov_b32_e32 v45, 0
	v_mov_b32_e32 v46, 0
	v_mov_b32_e32 v47, 0
	v_mov_b32_e32 v48, 0
	v_mov_b32_e32 v49, 0
	v_mov_b32_e32 v50, 0
	v_mov_b32_e32 v51, 0
.Lconv_nz31:
	v_lshlrev_b32_e32 v36, 16, v148
	v_and_b32_e32 v37, 0xffff0000, v148
	v_lshlrev_b32_e32 v38, 16, v149
	v_and_b32_e32 v39, 0xffff0000, v149
	v_lshlrev_b32_e32 v40, 16, v150
	v_and_b32_e32 v41, 0xffff0000, v150
	v_lshlrev_b32_e32 v42, 16, v151
	v_and_b32_e32 v43, 0xffff0000, v151
	v_lshlrev_b32_e32 v52, 16, v152
	v_and_b32_e32 v53, 0xffff0000, v152
	v_lshlrev_b32_e32 v54, 16, v153
	v_and_b32_e32 v55, 0xffff0000, v153
	v_lshlrev_b32_e32 v56, 16, v154
	v_and_b32_e32 v57, 0xffff0000, v154
	v_lshlrev_b32_e32 v58, 16, v155
	v_and_b32_e32 v59, 0xffff0000, v155
	v_pk_mul_f32 v[60:61], v[4:5], v[44:45]
	v_pk_mul_f32 v[62:63], v[6:7], v[46:47]
	v_pk_mul_f32 v[64:65], v[8:9], v[48:49]
	v_pk_mul_f32 v[66:67], v[10:11], v[50:51]
	v_pk_fma_f32 v[60:61], v[12:13], v[28:29], v[60:61]
	v_pk_fma_f32 v[62:63], v[14:15], v[30:31], v[62:63]
	v_pk_fma_f32 v[64:65], v[16:17], v[32:33], v[64:65]
	v_pk_fma_f32 v[66:67], v[18:19], v[34:35], v[66:67]
	v_pk_fma_f32 v[60:61], v[20:21], v[36:37], v[60:61]
	v_pk_fma_f32 v[62:63], v[22:23], v[38:39], v[62:63]
	v_pk_fma_f32 v[64:65], v[24:25], v[40:41], v[64:65]
	v_pk_fma_f32 v[66:67], v[26:27], v[42:43], v[66:67]
	v_pk_mul_f32 v[60:61], v[60:61], v[52:53]
	v_pk_mul_f32 v[62:63], v[62:63], v[54:55]
	v_pk_mul_f32 v[64:65], v[64:65], v[56:57]
	v_pk_mul_f32 v[66:67], v[66:67], v[58:59]
	v_cvt_pk_bf16_f32 v148, v60, v61
	v_cvt_pk_bf16_f32 v149, v62, v63
	v_cvt_pk_bf16_f32 v150, v64, v65
	v_cvt_pk_bf16_f32 v151, v66, v67
	global_store_dwordx4 v2, v[148:151], s[20:21]
	s_add_u32 s20, s20, 0x1000
	s_addc_u32 s21, s21, 0
	s_add_i32 s11, s11, 1
	s_cmp_eq_u32 s11, 0x1010
	s_cselect_b32 s11, 0, s11
	s_waitcnt vmcnt(10)
	s_cmp_eq_u32 s11, 0
	s_cbranch_scc0 .Lconv_nz32
	v_mov_b32_e32 v36, 0
	v_mov_b32_e32 v37, 0
	v_mov_b32_e32 v38, 0
	v_mov_b32_e32 v39, 0
	v_mov_b32_e32 v40, 0
	v_mov_b32_e32 v41, 0
	v_mov_b32_e32 v42, 0
	v_mov_b32_e32 v43, 0
	v_mov_b32_e32 v28, 0
	v_mov_b32_e32 v29, 0
	v_mov_b32_e32 v30, 0
	v_mov_b32_e32 v31, 0
	v_mov_b32_e32 v32, 0
	v_mov_b32_e32 v33, 0
	v_mov_b32_e32 v34, 0
	v_mov_b32_e32 v35, 0
.Lconv_nz32:
	v_lshlrev_b32_e32 v44, 16, v156
	v_and_b32_e32 v45, 0xffff0000, v156
	v_lshlrev_b32_e32 v46, 16, v157
	v_and_b32_e32 v47, 0xffff0000, v157
	v_lshlrev_b32_e32 v48, 16, v158
	v_and_b32_e32 v49, 0xffff0000, v158
	v_lshlrev_b32_e32 v50, 16, v159
	v_and_b32_e32 v51, 0xffff0000, v159
	v_lshlrev_b32_e32 v52, 16, v160
	v_and_b32_e32 v53, 0xffff0000, v160
	v_lshlrev_b32_e32 v54, 16, v161
	v_and_b32_e32 v55, 0xffff0000, v161
	v_lshlrev_b32_e32 v56, 16, v162
	v_and_b32_e32 v57, 0xffff0000, v162
	v_lshlrev_b32_e32 v58, 16, v163
	v_and_b32_e32 v59, 0xffff0000, v163
	v_pk_mul_f32 v[60:61], v[4:5], v[28:29]
	v_pk_mul_f32 v[62:63], v[6:7], v[30:31]
	v_pk_mul_f32 v[64:65], v[8:9], v[32:33]
	v_pk_mul_f32 v[66:67], v[10:11], v[34:35]
	v_pk_fma_f32 v[60:61], v[12:13], v[36:37], v[60:61]
	v_pk_fma_f32 v[62:63], v[14:15], v[38:39], v[62:63]
	v_pk_fma_f32 v[64:65], v[16:17], v[40:41], v[64:65]
	v_pk_fma_f32 v[66:67], v[18:19], v[42:43], v[66:67]
	v_pk_fma_f32 v[60:61], v[20:21], v[44:45], v[60:61]
	v_pk_fma_f32 v[62:63], v[22:23], v[46:47], v[62:63]
	v_pk_fma_f32 v[64:65], v[24:25], v[48:49], v[64:65]
	v_pk_fma_f32 v[66:67], v[26:27], v[50:51], v[66:67]
	v_pk_mul_f32 v[60:61], v[60:61], v[52:53]
	v_pk_mul_f32 v[62:63], v[62:63], v[54:55]
	v_pk_mul_f32 v[64:65], v[64:65], v[56:57]
	v_pk_mul_f32 v[66:67], v[66:67], v[58:59]
	v_cvt_pk_bf16_f32 v156, v60, v61
	v_cvt_pk_bf16_f32 v157, v62, v63
	v_cvt_pk_bf16_f32 v158, v64, v65
	v_cvt_pk_bf16_f32 v159, v66, v67
	global_store_dwordx4 v2, v[156:159], s[20:21]
	s_add_u32 s20, s20, 0x1000
	s_addc_u32 s21, s21, 0
	s_add_i32 s11, s11, 1
	s_cmp_eq_u32 s11, 0x1010
	s_cselect_b32 s11, 0, s11
